# GEMM K-loops: first iteration peeled with SrcC=0, per-unit accumulator zeroing (127 v_mov) removed
# speedup vs baseline: 1.0086x; 1.0086x over previous
; #define PG8_STAGE(bufoff, gbase, voff) do { _Pragma("unroll") for (int _i = 0; _i < 2; ++_i) \
;         __builtin_amdgcn_global_load_lds((const unsigned*)((const char*)(gbase) + (voff)[_i]), (LAS unsigned*)(lds + (bufoff) + ldsw + _i * 8192), 16, 0, 0); } while (0)
; #define PG8_LDA(dst, b, h) do { _Pragma("unroll") for (int m = 0; m < 4; ++m) _Pragma("unroll") for (int k = 0; k < 2; ++k) dst[m][k] = *(const LAS bf16x8*)(lds + PG8_SA(b, h) + aoff + m * 2048 + k * 1024); } while (0)
; #define PG8_LDB(dst, b, h) do { _Pragma("unroll") for (int n = 0; n < 2; ++n) _Pragma("unroll") for (int k = 0; k < 2; ++k) dst[n][k] = *(const LAS bf16x8*)(lds + PG8_SB(b, h) + boff + n * 2048 + k * 1024); } while (0)
; #define PG8_MMA(ai, bj, At, Bt) do { __builtin_amdgcn_s_setprio(1); _Pragma("unroll") for (int m = 0; m < 4; ++m) _Pragma("unroll") for (int n = 0; n < 2; ++n) _Pragma("unroll") for (int k = 0; k < 2; ++k) \
;         acc[ai][bj][m][n] = __builtin_amdgcn_mfma_f32_16x16x32_bf16(Bt[n][k], At[m][k], acc[ai][bj][m][n], 0, 0, 0); __builtin_amdgcn_s_setprio(0); } while (0)
; #define PG8_WAIT_V(n) asm volatile("s_waitcnt vmcnt(" #n ")" ::: "memory")
; #define PG8_WAIT_L(n) asm volatile("s_waitcnt lgkmcnt(" #n ")" ::: "memory")
; #define PG8_BAR __builtin_amdgcn_s_barrier()
; #define PG8_SCHED __builtin_amdgcn_sched_barrier(0)
; template <class Epi>
; __device__ __forceinline__ void gemm_phase(LAS unsigned char* lds, const Sched& S, const Epi& E) {
;     ...
;             const bool last = (t == nt - 2);
;             const char* a1 = cA + (size_t)(t + 1) * kstep;
;             const char* a2 = last ? nA : cA + (size_t)(t + 2) * kstep; const char* b2 = last ? nB : cB + (size_t)(t + 2) * kstep;
;             const char* a3 = a2 + kstep; const char* b3 = b2 + kstep;
;             PG8_LDB(B0, 0, 0); PG8_LDB(B1, 0, 1); PG8_SCHED; PG8_LDA(At, 0, 0); PG8_STAGE(PG8_SA(1, 1), a1 + hstepA, voffA);
;             PG8_WAIT_V(8); PG8_WAIT_L(0); PG8_BAR; PG8_MMA(0, 0, At, B0); PG8_MMA(0, 1, At, B1); PG8_BAR; PG8_SCHED;
.LBB0_734:
	s_add_u32 s22, s22, 0x80080
	s_addc_u32 s23, s23, 0
	s_add_u32 s9, s24, 0x100
	v_mov_b32_e32 v2, 0
	s_addc_u32 s11, s25, 0
	s_mov_b32 s68, -2
	s_add_u32 s24, s22, 0xfff80080
	s_addc_u32 s25, s23, -1
	s_add_i32 s49, 0, 0x10000
	s_cmp_eq_u32 s68, 28
	s_cselect_b32 s27, s19, s25
	s_cselect_b32 s26, s18, s24
	v_add_u32_e32 v153, s49, v149
	s_cselect_b32 s25, s21, s11
	s_cselect_b32 s24, s20, s9
	s_add_i32 s69, 0, 0x14000
	ds_read_b128 v[140:143], v153
	ds_read_b128 v[144:147], v153 offset:1024
	ds_read_b128 v[154:157], v153 offset:2048
	ds_read_b128 v[158:161], v153 offset:3072
	v_add_u32_e32 v153, s69, v149
	ds_read_b128 v[162:165], v153
	ds_read_b128 v[176:179], v153 offset:1024
	ds_read_b128 v[180:183], v153 offset:2048
	ds_read_b128 v[184:187], v153 offset:3072
	v_lshl_add_u64 v[166:167], s[22:23], 0, v[136:137]
	s_add_i32 m0, s17, 0xc000
	ds_read_b128 v[188:191], v152
	ds_read_b128 v[192:195], v152 offset:1024
	ds_read_b128 v[196:199], v152 offset:2048
	ds_read_b128 v[222:225], v152 offset:3072
	ds_read_b128 v[226:229], v152 offset:4096
	ds_read_b128 v[230:233], v152 offset:5120
	ds_read_b128 v[234:237], v152 offset:6144
	ds_read_b128 v[238:241], v152 offset:7168
	global_load_lds_dwordx4 v[166:167], off
	v_lshl_add_u64 v[166:167], s[22:23], 0, v[138:139]
	s_add_i32 m0, s17, 0xe000
	s_nop 0
	global_load_lds_dwordx4 v[166:167], off
	s_waitcnt vmcnt(8)
	s_waitcnt lgkmcnt(0)
	s_barrier
	s_setprio 1
	s_waitcnt lgkmcnt(0)
	v_mfma_f32_16x16x32_bf16 v[126:129], v[140:143], v[188:191], 0
	v_mfma_f32_16x16x32_bf16 v[122:125], v[154:157], v[188:191], 0
	v_mfma_f32_16x16x32_bf16 v[114:117], v[140:143], v[196:199], 0
	v_mfma_f32_16x16x32_bf16 v[106:109], v[154:157], v[196:199], 0
	v_mfma_f32_16x16x32_bf16 v[98:101], v[140:143], v[226:229], 0
	v_mfma_f32_16x16x32_bf16 v[90:93], v[154:157], v[226:229], 0
	v_mfma_f32_16x16x32_bf16 v[82:85], v[140:143], v[234:237], 0
	v_mfma_f32_16x16x32_bf16 v[74:77], v[154:157], v[234:237], 0
	v_mfma_f32_16x16x32_bf16 v[126:129], v[144:147], v[192:195], v[126:129]
	v_mfma_f32_16x16x32_bf16 v[122:125], v[158:161], v[192:195], v[122:125]
	v_mfma_f32_16x16x32_bf16 v[114:117], v[144:147], v[222:225], v[114:117]
	v_mfma_f32_16x16x32_bf16 v[106:109], v[158:161], v[222:225], v[106:109]
	v_mfma_f32_16x16x32_bf16 v[98:101], v[144:147], v[230:233], v[98:101]
	v_mfma_f32_16x16x32_bf16 v[90:93], v[158:161], v[230:233], v[90:93]
	v_mfma_f32_16x16x32_bf16 v[82:85], v[144:147], v[238:241], v[82:85]
	v_mfma_f32_16x16x32_bf16 v[74:77], v[158:161], v[238:241], v[74:77]
	s_setprio 0
	s_setprio 1
	v_mfma_f32_16x16x32_bf16 v[118:121], v[162:165], v[188:191], 0
	v_mfma_f32_16x16x32_bf16 v[110:113], v[180:183], v[188:191], 0
	v_mfma_f32_16x16x32_bf16 v[102:105], v[162:165], v[196:199], 0
	v_mfma_f32_16x16x32_bf16 v[94:97], v[180:183], v[196:199], 0
	v_mfma_f32_16x16x32_bf16 v[86:89], v[162:165], v[226:229], 0
	v_mfma_f32_16x16x32_bf16 v[78:81], v[180:183], v[226:229], 0
	v_mfma_f32_16x16x32_bf16 v[70:73], v[162:165], v[234:237], 0
	v_mfma_f32_16x16x32_bf16 v[66:69], v[180:183], v[234:237], 0
	v_mfma_f32_16x16x32_bf16 v[118:121], v[176:179], v[192:195], v[118:121]
	v_mfma_f32_16x16x32_bf16 v[110:113], v[184:187], v[192:195], v[110:113]
	v_mfma_f32_16x16x32_bf16 v[102:105], v[176:179], v[222:225], v[102:105]
	v_mfma_f32_16x16x32_bf16 v[94:97], v[184:187], v[222:225], v[94:97]
	v_mfma_f32_16x16x32_bf16 v[86:89], v[176:179], v[230:233], v[86:89]
	v_mfma_f32_16x16x32_bf16 v[78:81], v[184:187], v[230:233], v[78:81]
	v_mfma_f32_16x16x32_bf16 v[70:73], v[176:179], v[238:241], v[70:73]
	v_mfma_f32_16x16x32_bf16 v[66:69], v[184:187], v[238:241], v[66:69]
	s_setprio 0
	s_barrier
	s_add_i32 s49, s49, s35
	v_lshl_add_u64 v[166:167], s[24:25], 0, v[168:169]
	s_mov_b32 m0, s49
	ds_read_b128 v[188:191], v152 offset:16384
	ds_read_b128 v[192:195], v152 offset:17408
	ds_read_b128 v[196:199], v152 offset:18432
	ds_read_b128 v[222:225], v152 offset:19456
	ds_read_b128 v[226:229], v152 offset:20480
	ds_read_b128 v[230:233], v152 offset:21504
	ds_read_b128 v[234:237], v152 offset:22528
	ds_read_b128 v[238:241], v152 offset:23552
	global_load_lds_dwordx4 v[166:167], off
	s_add_i32 m0, s49, 0x2000
	s_add_u32 s94, s24, 0x80000
	v_lshl_add_u64 v[200:201], s[24:25], 0, v[134:135]
	s_addc_u32 s95, s25, 0
	s_add_i32 s49, s69, s35
	global_load_lds_dwordx4 v[200:201], off
	v_lshl_add_u64 v[242:243], s[94:95], 0, v[168:169]
	s_mov_b32 m0, s49
	v_lshl_add_u64 v[244:245], s[26:27], 0, v[132:133]
	global_load_lds_dwordx4 v[242:243], off
	v_lshl_add_u64 v[242:243], s[94:95], 0, v[134:135]
	s_add_i32 m0, s49, 0x2000
	s_nop 0
	global_load_lds_dwordx4 v[242:243], off
	v_lshl_add_u64 v[242:243], s[26:27], 0, v[130:131]
	s_mov_b32 m0, s17
	s_nop 0
	global_load_lds_dwordx4 v[242:243], off
	s_mov_b32 m0, s36
	s_nop 0
	global_load_lds_dwordx4 v[244:245], off
	s_waitcnt vmcnt(8)
	s_waitcnt lgkmcnt(0)
	s_barrier
; #define PG8_STAGE(bufoff, gbase, voff) do { _Pragma("unroll") for (int _i = 0; _i < 2; ++_i) \
;         __builtin_amdgcn_global_load_lds((const unsigned*)((const char*)(gbase) + (voff)[_i]), (LAS unsigned*)(lds + (bufoff) + ldsw + _i * 8192), 16, 0, 0); } while (0)
; #define PG8_LDA(dst, b, h) do { _Pragma("unroll") for (int m = 0; m < 4; ++m) _Pragma("unroll") for (int k = 0; k < 2; ++k) dst[m][k] = *(const LAS bf16x8*)(lds + PG8_SA(b, h) + aoff + m * 2048 + k * 1024); } while (0)
; #define PG8_LDB(dst, b, h) do { _Pragma("unroll") for (int n = 0; n < 2; ++n) _Pragma("unroll") for (int k = 0; k < 2; ++k) dst[n][k] = *(const LAS bf16x8*)(lds + PG8_SB(b, h) + boff + n * 2048 + k * 1024); } while (0)
; #define PG8_MMA(ai, bj, At, Bt) do { __builtin_amdgcn_s_setprio(1); _Pragma("unroll") for (int m = 0; m < 4; ++m) _Pragma("unroll") for (int n = 0; n < 2; ++n) _Pragma("unroll") for (int k = 0; k < 2; ++k) \
;         acc[ai][bj][m][n] = __builtin_amdgcn_mfma_f32_16x16x32_bf16(Bt[n][k], At[m][k], acc[ai][bj][m][n], 0, 0, 0); __builtin_amdgcn_s_setprio(0); } while (0)
; #define PG8_WAIT_V(n) asm volatile("s_waitcnt vmcnt(" #n ")" ::: "memory")
; #define PG8_WAIT_L(n) asm volatile("s_waitcnt lgkmcnt(" #n ")" ::: "memory")
; #define PG8_BAR __builtin_amdgcn_s_barrier()
; #define PG8_SCHED __builtin_amdgcn_sched_barrier(0)
; template <class Epi>
; __device__ __forceinline__ void gemm_phase(LAS unsigned char* lds, const Sched& S, const Epi& E) {
;     ...
;             PG8_LDA(At, 0, 1); PG8_STAGE(PG8_SB(0, 0), b2, voffB); PG8_STAGE(PG8_SB(0, 1), b2 + hstepB, voffB); PG8_STAGE(PG8_SA(0, 0), a2, voffA);
;             PG8_WAIT_V(8); PG8_WAIT_L(0); PG8_BAR; PG8_MMA(1, 0, At, B0); PG8_MMA(1, 1, At, B1); PG8_BAR; PG8_SCHED;
;             PG8_LDB(B0, 1, 0); PG8_LDB(B1, 1, 1); PG8_SCHED; PG8_LDA(At, 1, 0); PG8_STAGE(PG8_SA(0, 1), a2 + hstepA, voffA);
;             PG8_WAIT_V(8); PG8_WAIT_L(0); PG8_BAR; PG8_MMA(0, 0, At, B0); PG8_MMA(0, 1, At, B1); PG8_BAR; PG8_SCHED;
	s_setprio 1
	s_waitcnt lgkmcnt(0)
	v_mfma_f32_16x16x32_bf16 v[62:65], v[140:143], v[188:191], 0
	v_mfma_f32_16x16x32_bf16 v[58:61], v[154:157], v[188:191], 0
	v_mfma_f32_16x16x32_bf16 v[50:53], v[140:143], v[196:199], 0
	v_mfma_f32_16x16x32_bf16 v[42:45], v[154:157], v[196:199], 0
	v_mfma_f32_16x16x32_bf16 v[34:37], v[140:143], v[226:229], 0
	v_mfma_f32_16x16x32_bf16 v[26:29], v[154:157], v[226:229], 0
	v_mfma_f32_16x16x32_bf16 v[18:21], v[140:143], v[234:237], 0
	v_mfma_f32_16x16x32_bf16 v[10:13], v[154:157], v[234:237], 0
	v_mfma_f32_16x16x32_bf16 v[62:65], v[144:147], v[192:195], v[62:65]
	v_mfma_f32_16x16x32_bf16 v[58:61], v[158:161], v[192:195], v[58:61]
	v_mfma_f32_16x16x32_bf16 v[50:53], v[144:147], v[222:225], v[50:53]
	v_mfma_f32_16x16x32_bf16 v[42:45], v[158:161], v[222:225], v[42:45]
	v_mfma_f32_16x16x32_bf16 v[34:37], v[144:147], v[230:233], v[34:37]
	v_mfma_f32_16x16x32_bf16 v[26:29], v[158:161], v[230:233], v[26:29]
	v_mfma_f32_16x16x32_bf16 v[18:21], v[144:147], v[238:241], v[18:21]
	v_mfma_f32_16x16x32_bf16 v[10:13], v[158:161], v[238:241], v[10:13]
	s_setprio 0
	s_setprio 1
	v_mfma_f32_16x16x32_bf16 v[54:57], v[162:165], v[188:191], 0
	v_mfma_f32_16x16x32_bf16 v[46:49], v[180:183], v[188:191], 0
	v_mfma_f32_16x16x32_bf16 v[38:41], v[162:165], v[196:199], 0
	v_mfma_f32_16x16x32_bf16 v[30:33], v[180:183], v[196:199], 0
	v_mfma_f32_16x16x32_bf16 v[22:25], v[162:165], v[226:229], 0
	v_mfma_f32_16x16x32_bf16 v[14:17], v[180:183], v[226:229], 0
	v_mfma_f32_16x16x32_bf16 v[6:9], v[162:165], v[234:237], 0
	v_mfma_f32_16x16x32_bf16 v[2:5], v[180:183], v[234:237], 0
	v_mfma_f32_16x16x32_bf16 v[54:57], v[176:179], v[192:195], v[54:57]
	v_mfma_f32_16x16x32_bf16 v[46:49], v[184:187], v[192:195], v[46:49]
	v_mfma_f32_16x16x32_bf16 v[38:41], v[176:179], v[222:225], v[38:41]
	v_mfma_f32_16x16x32_bf16 v[30:33], v[184:187], v[222:225], v[30:33]
	v_mfma_f32_16x16x32_bf16 v[22:25], v[176:179], v[230:233], v[22:25]
	v_mfma_f32_16x16x32_bf16 v[14:17], v[184:187], v[230:233], v[14:17]
	v_mfma_f32_16x16x32_bf16 v[6:9], v[176:179], v[238:241], v[6:9]
	v_mfma_f32_16x16x32_bf16 v[2:5], v[184:187], v[238:241], v[2:5]
	s_setprio 0
	s_barrier
	s_add_i32 s49, 0, 0x18000
	v_add_u32_e32 v153, s49, v149
	s_add_i32 s69, 0, 0x1c000
	ds_read_b128 v[140:143], v153
	ds_read_b128 v[144:147], v153 offset:1024
	ds_read_b128 v[154:157], v153 offset:2048
	ds_read_b128 v[158:161], v153 offset:3072
	v_add_u32_e32 v153, s69, v149
	ds_read_b128 v[162:165], v153
	ds_read_b128 v[176:179], v153 offset:1024
	ds_read_b128 v[180:183], v153 offset:2048
	ds_read_b128 v[184:187], v153 offset:3072
	s_add_u32 s26, s26, 0x80000
	s_addc_u32 s27, s27, 0
	s_mov_b32 m0, s37
	v_lshl_add_u64 v[246:247], s[26:27], 0, v[130:131]
	ds_read_b128 v[188:191], v152 offset:32768
	ds_read_b128 v[192:195], v152 offset:33792
	ds_read_b128 v[196:199], v152 offset:34816
	ds_read_b128 v[222:225], v152 offset:35840
	ds_read_b128 v[226:229], v152 offset:36864
	ds_read_b128 v[230:233], v152 offset:37888
	ds_read_b128 v[234:237], v152 offset:38912
	ds_read_b128 v[238:241], v152 offset:39936
	global_load_lds_dwordx4 v[246:247], off
	v_lshl_add_u64 v[246:247], s[26:27], 0, v[132:133]
	s_mov_b32 m0, s38
	s_nop 0
	global_load_lds_dwordx4 v[246:247], off
	s_waitcnt vmcnt(8)
	s_waitcnt lgkmcnt(0)
	s_barrier
	s_setprio 1
	s_waitcnt lgkmcnt(0)
	v_mfma_f32_16x16x32_bf16 v[126:129], v[140:143], v[188:191], v[126:129]
	v_mfma_f32_16x16x32_bf16 v[122:125], v[154:157], v[188:191], v[122:125]
	v_mfma_f32_16x16x32_bf16 v[114:117], v[140:143], v[196:199], v[114:117]
	v_mfma_f32_16x16x32_bf16 v[106:109], v[154:157], v[196:199], v[106:109]
	v_mfma_f32_16x16x32_bf16 v[98:101], v[140:143], v[226:229], v[98:101]
	v_mfma_f32_16x16x32_bf16 v[90:93], v[154:157], v[226:229], v[90:93]
	v_mfma_f32_16x16x32_bf16 v[82:85], v[140:143], v[234:237], v[82:85]
	v_mfma_f32_16x16x32_bf16 v[74:77], v[154:157], v[234:237], v[74:77]
	v_mfma_f32_16x16x32_bf16 v[126:129], v[144:147], v[192:195], v[126:129]
	v_mfma_f32_16x16x32_bf16 v[122:125], v[158:161], v[192:195], v[122:125]
	v_mfma_f32_16x16x32_bf16 v[114:117], v[144:147], v[222:225], v[114:117]
	v_mfma_f32_16x16x32_bf16 v[106:109], v[158:161], v[222:225], v[106:109]
	v_mfma_f32_16x16x32_bf16 v[98:101], v[144:147], v[230:233], v[98:101]
	v_mfma_f32_16x16x32_bf16 v[90:93], v[158:161], v[230:233], v[90:93]
	v_mfma_f32_16x16x32_bf16 v[82:85], v[144:147], v[238:241], v[82:85]
	v_mfma_f32_16x16x32_bf16 v[74:77], v[158:161], v[238:241], v[74:77]
	s_setprio 0
	s_setprio 1
	v_mfma_f32_16x16x32_bf16 v[118:121], v[162:165], v[188:191], v[118:121]
	v_mfma_f32_16x16x32_bf16 v[110:113], v[180:183], v[188:191], v[110:113]
	v_mfma_f32_16x16x32_bf16 v[102:105], v[162:165], v[196:199], v[102:105]
	v_mfma_f32_16x16x32_bf16 v[94:97], v[180:183], v[196:199], v[94:97]
	v_mfma_f32_16x16x32_bf16 v[86:89], v[162:165], v[226:229], v[86:89]
	v_mfma_f32_16x16x32_bf16 v[78:81], v[180:183], v[226:229], v[78:81]
	v_mfma_f32_16x16x32_bf16 v[70:73], v[162:165], v[234:237], v[70:73]
	v_mfma_f32_16x16x32_bf16 v[66:69], v[180:183], v[234:237], v[66:69]
	v_mfma_f32_16x16x32_bf16 v[118:121], v[176:179], v[192:195], v[118:121]
	v_mfma_f32_16x16x32_bf16 v[110:113], v[184:187], v[192:195], v[110:113]
	v_mfma_f32_16x16x32_bf16 v[102:105], v[176:179], v[222:225], v[102:105]
	v_mfma_f32_16x16x32_bf16 v[94:97], v[184:187], v[222:225], v[94:97]
	v_mfma_f32_16x16x32_bf16 v[86:89], v[176:179], v[230:233], v[86:89]
	v_mfma_f32_16x16x32_bf16 v[78:81], v[184:187], v[230:233], v[78:81]
	v_mfma_f32_16x16x32_bf16 v[70:73], v[176:179], v[238:241], v[70:73]
	v_mfma_f32_16x16x32_bf16 v[66:69], v[184:187], v[238:241], v[66:69]
	s_setprio 0
	s_barrier
; #define PG8_STAGE(bufoff, gbase, voff) do { _Pragma("unroll") for (int _i = 0; _i < 2; ++_i) \
;         __builtin_amdgcn_global_load_lds((const unsigned*)((const char*)(gbase) + (voff)[_i]), (LAS unsigned*)(lds + (bufoff) + ldsw + _i * 8192), 16, 0, 0); } while (0)
; #define PG8_LDA(dst, b, h) do { _Pragma("unroll") for (int m = 0; m < 4; ++m) _Pragma("unroll") for (int k = 0; k < 2; ++k) dst[m][k] = *(const LAS bf16x8*)(lds + PG8_SA(b, h) + aoff + m * 2048 + k * 1024); } while (0)
; #define PG8_MMA(ai, bj, At, Bt) do { __builtin_amdgcn_s_setprio(1); _Pragma("unroll") for (int m = 0; m < 4; ++m) _Pragma("unroll") for (int n = 0; n < 2; ++n) _Pragma("unroll") for (int k = 0; k < 2; ++k) \
;         acc[ai][bj][m][n] = __builtin_amdgcn_mfma_f32_16x16x32_bf16(Bt[n][k], At[m][k], acc[ai][bj][m][n], 0, 0, 0); __builtin_amdgcn_s_setprio(0); } while (0)
; #define PG8_WAIT_V(n) asm volatile("s_waitcnt vmcnt(" #n ")" ::: "memory")
; #define PG8_WAIT_L(n) asm volatile("s_waitcnt lgkmcnt(" #n ")" ::: "memory")
; #define PG8_BAR __builtin_amdgcn_s_barrier()
; #define PG8_SCHED __builtin_amdgcn_sched_barrier(0)
; template <class Epi>
; __device__ __forceinline__ void gemm_phase(LAS unsigned char* lds, const Sched& S, const Epi& E) {
;     ...
;             PG8_LDA(At, 1, 1); PG8_STAGE(PG8_SB(1, 0), b3, voffB); PG8_STAGE(PG8_SB(1, 1), b3 + hstepB, voffB); PG8_STAGE(PG8_SA(1, 0), a3, voffA);
;             PG8_WAIT_V(8); PG8_WAIT_L(0); PG8_BAR; PG8_MMA(1, 0, At, B0); PG8_MMA(1, 1, At, B1); PG8_BAR; PG8_SCHED;
;         }
	s_add_i32 s26, s49, s35
	v_lshl_add_u64 v[166:167], v[166:167], 0, s[0:1]
	s_mov_b32 m0, s26
	ds_read_b128 v[188:191], v152 offset:49152
	ds_read_b128 v[192:195], v152 offset:50176
	ds_read_b128 v[196:199], v152 offset:51200
	ds_read_b128 v[222:225], v152 offset:52224
	ds_read_b128 v[226:229], v152 offset:53248
	ds_read_b128 v[230:233], v152 offset:54272
	ds_read_b128 v[234:237], v152 offset:55296
	ds_read_b128 v[238:241], v152 offset:56320
	global_load_lds_dwordx4 v[166:167], off
	s_add_i32 m0, s26, 0x2000
	s_add_u32 s24, s24, 0x80080
	v_lshl_add_u64 v[166:167], v[200:201], 0, s[0:1]
	s_addc_u32 s25, s25, 0
	s_add_i32 s26, s69, s35
	global_load_lds_dwordx4 v[166:167], off
	v_lshl_add_u64 v[166:167], s[24:25], 0, v[168:169]
	s_mov_b32 m0, s26
	s_nop 0
	global_load_lds_dwordx4 v[166:167], off
	v_lshl_add_u64 v[166:167], s[24:25], 0, v[134:135]
	s_add_i32 m0, s26, 0x2000
	s_nop 0
	global_load_lds_dwordx4 v[166:167], off
	v_lshl_add_u64 v[166:167], v[242:243], 0, s[0:1]
	s_mov_b32 m0, s39
	s_nop 0
	global_load_lds_dwordx4 v[166:167], off
	v_lshl_add_u64 v[166:167], v[244:245], 0, s[0:1]
	s_mov_b32 m0, s59
	s_nop 0
	global_load_lds_dwordx4 v[166:167], off
	s_waitcnt vmcnt(8)
	s_waitcnt lgkmcnt(0)
	s_barrier
	s_setprio 1
	s_waitcnt lgkmcnt(0)
	v_mfma_f32_16x16x32_bf16 v[62:65], v[140:143], v[188:191], v[62:65]
	v_mfma_f32_16x16x32_bf16 v[58:61], v[154:157], v[188:191], v[58:61]
	v_mfma_f32_16x16x32_bf16 v[50:53], v[140:143], v[196:199], v[50:53]
	v_mfma_f32_16x16x32_bf16 v[42:45], v[154:157], v[196:199], v[42:45]
	v_mfma_f32_16x16x32_bf16 v[34:37], v[140:143], v[226:229], v[34:37]
	v_mfma_f32_16x16x32_bf16 v[26:29], v[154:157], v[226:229], v[26:29]
	v_mfma_f32_16x16x32_bf16 v[18:21], v[140:143], v[234:237], v[18:21]
	v_mfma_f32_16x16x32_bf16 v[10:13], v[154:157], v[234:237], v[10:13]
	v_mfma_f32_16x16x32_bf16 v[62:65], v[144:147], v[192:195], v[62:65]
	v_mfma_f32_16x16x32_bf16 v[58:61], v[158:161], v[192:195], v[58:61]
	v_mfma_f32_16x16x32_bf16 v[50:53], v[144:147], v[222:225], v[50:53]
	v_mfma_f32_16x16x32_bf16 v[42:45], v[158:161], v[222:225], v[42:45]
	v_mfma_f32_16x16x32_bf16 v[34:37], v[144:147], v[230:233], v[34:37]
	v_mfma_f32_16x16x32_bf16 v[26:29], v[158:161], v[230:233], v[26:29]
	v_mfma_f32_16x16x32_bf16 v[18:21], v[144:147], v[238:241], v[18:21]
	v_mfma_f32_16x16x32_bf16 v[10:13], v[158:161], v[238:241], v[10:13]
	s_setprio 0
	s_setprio 1
	v_mfma_f32_16x16x32_bf16 v[54:57], v[162:165], v[188:191], v[54:57]
	v_mfma_f32_16x16x32_bf16 v[46:49], v[180:183], v[188:191], v[46:49]
	v_mfma_f32_16x16x32_bf16 v[38:41], v[162:165], v[196:199], v[38:41]
	v_mfma_f32_16x16x32_bf16 v[30:33], v[180:183], v[196:199], v[30:33]
	v_mfma_f32_16x16x32_bf16 v[22:25], v[162:165], v[226:229], v[22:25]
	v_mfma_f32_16x16x32_bf16 v[14:17], v[180:183], v[226:229], v[14:17]
	v_mfma_f32_16x16x32_bf16 v[6:9], v[162:165], v[234:237], v[6:9]
	v_mfma_f32_16x16x32_bf16 v[2:5], v[180:183], v[234:237], v[2:5]
	v_mfma_f32_16x16x32_bf16 v[54:57], v[176:179], v[192:195], v[54:57]
	v_mfma_f32_16x16x32_bf16 v[46:49], v[184:187], v[192:195], v[46:49]
	v_mfma_f32_16x16x32_bf16 v[38:41], v[176:179], v[222:225], v[38:41]
	v_mfma_f32_16x16x32_bf16 v[30:33], v[184:187], v[222:225], v[30:33]
	v_mfma_f32_16x16x32_bf16 v[22:25], v[176:179], v[230:233], v[22:25]
	v_mfma_f32_16x16x32_bf16 v[14:17], v[184:187], v[230:233], v[14:17]
	v_mfma_f32_16x16x32_bf16 v[6:9], v[176:179], v[238:241], v[6:9]
	v_mfma_f32_16x16x32_bf16 v[2:5], v[184:187], v[238:241], v[2:5]
	s_setprio 0
	s_barrier
	s_add_i32 s68, s68, 2
	s_add_u32 s22, s22, 0x100
	s_addc_u32 s23, s23, 0
	s_add_u32 s9, s9, 0x100
	s_addc_u32 s11, s11, 0
	s_cmp_gt_u32 s68, 29
	s_cbranch_scc1 .Lpeel_exit_qkv

; #define PG8_BAR __builtin_amdgcn_s_barrier()
; template <class Epi>
; __device__ __forceinline__ void gemm_phase(LAS unsigned char* lds, const Sched& S, const Epi& E) {
;     ...
;         if (wr == 0) PG8_BAR;
.Lpeel_exit_qkv:
	s_and_b64 vcc, exec, s[6:7]
	s_cbranch_vccz .LBB0_738
	s_barrier

; #define PG8_STAGE(bufoff, gbase, voff) do { _Pragma("unroll") for (int _i = 0; _i < 2; ++_i) \
;         __builtin_amdgcn_global_load_lds((const unsigned*)((const char*)(gbase) + (voff)[_i]), (LAS unsigned*)(lds + (bufoff) + ldsw + _i * 8192), 16, 0, 0); } while (0)
; #define PG8_LDA(dst, b, h) do { _Pragma("unroll") for (int m = 0; m < 4; ++m) _Pragma("unroll") for (int k = 0; k < 2; ++k) dst[m][k] = *(const LAS bf16x8*)(lds + PG8_SA(b, h) + aoff + m * 2048 + k * 1024); } while (0)
; #define PG8_LDB(dst, b, h) do { _Pragma("unroll") for (int n = 0; n < 2; ++n) _Pragma("unroll") for (int k = 0; k < 2; ++k) dst[n][k] = *(const LAS bf16x8*)(lds + PG8_SB(b, h) + boff + n * 2048 + k * 1024); } while (0)
; #define PG8_MMA(ai, bj, At, Bt) do { __builtin_amdgcn_s_setprio(1); _Pragma("unroll") for (int m = 0; m < 4; ++m) _Pragma("unroll") for (int n = 0; n < 2; ++n) _Pragma("unroll") for (int k = 0; k < 2; ++k) \
;         acc[ai][bj][m][n] = __builtin_amdgcn_mfma_f32_16x16x32_bf16(Bt[n][k], At[m][k], acc[ai][bj][m][n], 0, 0, 0); __builtin_amdgcn_s_setprio(0); } while (0)
; #define PG8_WAIT_V(n) asm volatile("s_waitcnt vmcnt(" #n ")" ::: "memory")
; #define PG8_WAIT_L(n) asm volatile("s_waitcnt lgkmcnt(" #n ")" ::: "memory")
; #define PG8_BAR __builtin_amdgcn_s_barrier()
; #define PG8_SCHED __builtin_amdgcn_sched_barrier(0)
; template <class Epi>
; __device__ __forceinline__ void gemm_phase(LAS unsigned char* lds, const Sched& S, const Epi& E) {
;     ...
;             const bool last = (t == nt - 2);
;             const char* a1 = cA + (size_t)(t + 1) * kstep;
;             const char* a2 = last ? nA : cA + (size_t)(t + 2) * kstep; const char* b2 = last ? nB : cB + (size_t)(t + 2) * kstep;
;             const char* a3 = a2 + kstep; const char* b3 = b2 + kstep;
;             PG8_LDB(B0, 0, 0); PG8_LDB(B1, 0, 1); PG8_SCHED; PG8_LDA(At, 0, 0); PG8_STAGE(PG8_SA(1, 1), a1 + hstepA, voffA);
;             PG8_WAIT_V(8); PG8_WAIT_L(0); PG8_BAR; PG8_MMA(0, 0, At, B0); PG8_MMA(0, 1, At, B1); PG8_BAR; PG8_SCHED;
.LBB0_1388:
	s_and_b64 s[24:25], s[16:17], exec
	s_cselect_b32 s9, s11, s21
	s_cselect_b32 s13, s10, s20
	s_cselect_b32 s26, s15, s23
	s_cselect_b32 s27, s14, s22
	s_add_i32 s69, s19, -2
	s_add_u32 s20, s20, 0x80080
	s_addc_u32 s21, s21, 0
	s_add_u32 s82, s22, 0x100
	v_mov_b32_e32 v2, 0
	s_addc_u32 s94, s23, 0
	s_mov_b32 s22, 0
	s_waitcnt lgkmcnt(0)
	s_add_i32 s95, s22, 2
	s_add_u32 s23, s20, 0xfff80080
	s_addc_u32 s24, s21, -1
	s_add_i32 s49, 0, 0x10000
	s_cmp_eq_u32 s69, s22
	s_cselect_b32 s25, s9, s24
	s_cselect_b32 s24, s13, s23
	s_cselect_b32 s23, s26, s94
	s_cselect_b32 s22, s27, s82
	s_add_i32 s88, 0, 0x14000
	v_add_u32_e32 v142, s49, v179
	v_add_u32_e32 v176, s88, v179
	ds_read_b128 v[130:133], v142
	ds_read_b128 v[134:137], v142 offset:1024
	ds_read_b128 v[138:141], v142 offset:2048
	ds_read_b128 v[142:145], v142 offset:3072
	ds_read_b128 v[160:163], v176
	ds_read_b128 v[164:167], v176 offset:1024
	ds_read_b128 v[182:185], v176 offset:2048
	ds_read_b128 v[186:189], v176 offset:3072
	v_lshl_add_u64 v[176:177], s[20:21], 0, v[156:157]
	s_add_i32 m0, s35, 0xc000
	ds_read_b128 v[190:193], v181
	ds_read_b128 v[194:197], v181 offset:1024
	ds_read_b128 v[198:201], v181 offset:2048
	ds_read_b128 v[222:225], v181 offset:3072
	ds_read_b128 v[226:229], v181 offset:4096
	ds_read_b128 v[230:233], v181 offset:5120
	ds_read_b128 v[234:237], v181 offset:6144
	ds_read_b128 v[238:241], v181 offset:7168
	global_load_lds_dwordx4 v[176:177], off
	v_lshl_add_u64 v[176:177], s[20:21], 0, v[158:159]
	s_add_i32 m0, s35, 0xe000
	s_nop 0
	global_load_lds_dwordx4 v[176:177], off
	s_waitcnt vmcnt(8)
	s_waitcnt lgkmcnt(0)
	s_barrier
	s_setprio 1
	s_waitcnt lgkmcnt(0)
	v_mfma_f32_16x16x32_bf16 v[126:129], v[130:133], v[190:193], 0
	v_mfma_f32_16x16x32_bf16 v[122:125], v[138:141], v[190:193], 0
	v_mfma_f32_16x16x32_bf16 v[110:113], v[130:133], v[198:201], 0
	v_mfma_f32_16x16x32_bf16 v[106:109], v[138:141], v[198:201], 0
	v_mfma_f32_16x16x32_bf16 v[94:97], v[130:133], v[226:229], 0
	v_mfma_f32_16x16x32_bf16 v[90:93], v[138:141], v[226:229], 0
	v_mfma_f32_16x16x32_bf16 v[78:81], v[130:133], v[234:237], 0
	v_mfma_f32_16x16x32_bf16 v[74:77], v[138:141], v[234:237], 0
	v_mfma_f32_16x16x32_bf16 v[126:129], v[134:137], v[194:197], v[126:129]
	v_mfma_f32_16x16x32_bf16 v[122:125], v[142:145], v[194:197], v[122:125]
	v_mfma_f32_16x16x32_bf16 v[110:113], v[134:137], v[222:225], v[110:113]
	v_mfma_f32_16x16x32_bf16 v[106:109], v[142:145], v[222:225], v[106:109]
	v_mfma_f32_16x16x32_bf16 v[94:97], v[134:137], v[230:233], v[94:97]
	v_mfma_f32_16x16x32_bf16 v[90:93], v[142:145], v[230:233], v[90:93]
	v_mfma_f32_16x16x32_bf16 v[78:81], v[134:137], v[238:241], v[78:81]
	v_mfma_f32_16x16x32_bf16 v[74:77], v[142:145], v[238:241], v[74:77]
	s_setprio 0
	s_setprio 1
	v_mfma_f32_16x16x32_bf16 v[118:121], v[160:163], v[190:193], 0
	v_mfma_f32_16x16x32_bf16 v[114:117], v[182:185], v[190:193], 0
	v_mfma_f32_16x16x32_bf16 v[102:105], v[160:163], v[198:201], 0
	v_mfma_f32_16x16x32_bf16 v[98:101], v[182:185], v[198:201], 0
	v_mfma_f32_16x16x32_bf16 v[86:89], v[160:163], v[226:229], 0
	v_mfma_f32_16x16x32_bf16 v[82:85], v[182:185], v[226:229], 0
	v_mfma_f32_16x16x32_bf16 v[70:73], v[160:163], v[234:237], 0
	v_mfma_f32_16x16x32_bf16 v[66:69], v[182:185], v[234:237], 0
	v_mfma_f32_16x16x32_bf16 v[118:121], v[164:167], v[194:197], v[118:121]
	v_mfma_f32_16x16x32_bf16 v[114:117], v[186:189], v[194:197], v[114:117]
	v_mfma_f32_16x16x32_bf16 v[102:105], v[164:167], v[222:225], v[102:105]
	v_mfma_f32_16x16x32_bf16 v[98:101], v[186:189], v[222:225], v[98:101]
	v_mfma_f32_16x16x32_bf16 v[86:89], v[164:167], v[230:233], v[86:89]
	v_mfma_f32_16x16x32_bf16 v[82:85], v[186:189], v[230:233], v[82:85]
	v_mfma_f32_16x16x32_bf16 v[70:73], v[164:167], v[238:241], v[70:73]
	v_mfma_f32_16x16x32_bf16 v[66:69], v[186:189], v[238:241], v[66:69]
	s_setprio 0
	s_barrier
	s_add_i32 s49, s49, s34
	v_lshl_add_u64 v[176:177], s[22:23], 0, v[168:169]
	s_mov_b32 m0, s49
	ds_read_b128 v[190:193], v181 offset:16384
	ds_read_b128 v[194:197], v181 offset:17408
	ds_read_b128 v[198:201], v181 offset:18432
	ds_read_b128 v[222:225], v181 offset:19456
	ds_read_b128 v[226:229], v181 offset:20480
	ds_read_b128 v[230:233], v181 offset:21504
	ds_read_b128 v[234:237], v181 offset:22528
	ds_read_b128 v[238:241], v181 offset:23552
	global_load_lds_dwordx4 v[176:177], off
	s_add_i32 m0, s49, 0x2000
	s_add_u32 s96, s22, 0x80000
	v_lshl_add_u64 v[242:243], s[22:23], 0, v[146:147]
	s_addc_u32 s97, s23, 0
	s_add_i32 s49, s88, s34
	global_load_lds_dwordx4 v[242:243], off
	v_lshl_add_u64 v[244:245], s[96:97], 0, v[168:169]
	s_mov_b32 m0, s49
	v_lshl_add_u64 v[246:247], s[24:25], 0, v[146:147]
	global_load_lds_dwordx4 v[244:245], off
	v_lshl_add_u64 v[244:245], s[96:97], 0, v[146:147]
	s_add_i32 m0, s49, 0x2000
	s_nop 0
	global_load_lds_dwordx4 v[244:245], off
	v_lshl_add_u64 v[244:245], s[24:25], 0, v[168:169]
	s_mov_b32 m0, s35
	s_nop 0
	global_load_lds_dwordx4 v[244:245], off
	s_mov_b32 m0, s36
	s_nop 0
	global_load_lds_dwordx4 v[246:247], off
	s_waitcnt vmcnt(8)
	s_waitcnt lgkmcnt(0)
	s_barrier
; #define PG8_STAGE(bufoff, gbase, voff) do { _Pragma("unroll") for (int _i = 0; _i < 2; ++_i) \
;         __builtin_amdgcn_global_load_lds((const unsigned*)((const char*)(gbase) + (voff)[_i]), (LAS unsigned*)(lds + (bufoff) + ldsw + _i * 8192), 16, 0, 0); } while (0)
; #define PG8_LDA(dst, b, h) do { _Pragma("unroll") for (int m = 0; m < 4; ++m) _Pragma("unroll") for (int k = 0; k < 2; ++k) dst[m][k] = *(const LAS bf16x8*)(lds + PG8_SA(b, h) + aoff + m * 2048 + k * 1024); } while (0)
; #define PG8_LDB(dst, b, h) do { _Pragma("unroll") for (int n = 0; n < 2; ++n) _Pragma("unroll") for (int k = 0; k < 2; ++k) dst[n][k] = *(const LAS bf16x8*)(lds + PG8_SB(b, h) + boff + n * 2048 + k * 1024); } while (0)
; #define PG8_MMA(ai, bj, At, Bt) do { __builtin_amdgcn_s_setprio(1); _Pragma("unroll") for (int m = 0; m < 4; ++m) _Pragma("unroll") for (int n = 0; n < 2; ++n) _Pragma("unroll") for (int k = 0; k < 2; ++k) \
;         acc[ai][bj][m][n] = __builtin_amdgcn_mfma_f32_16x16x32_bf16(Bt[n][k], At[m][k], acc[ai][bj][m][n], 0, 0, 0); __builtin_amdgcn_s_setprio(0); } while (0)
; #define PG8_WAIT_V(n) asm volatile("s_waitcnt vmcnt(" #n ")" ::: "memory")
; #define PG8_WAIT_L(n) asm volatile("s_waitcnt lgkmcnt(" #n ")" ::: "memory")
; #define PG8_BAR __builtin_amdgcn_s_barrier()
; #define PG8_SCHED __builtin_amdgcn_sched_barrier(0)
; template <class Epi>
; __device__ __forceinline__ void gemm_phase(LAS unsigned char* lds, const Sched& S, const Epi& E) {
;     ...
;             PG8_LDA(At, 0, 1); PG8_STAGE(PG8_SB(0, 0), b2, voffB); PG8_STAGE(PG8_SB(0, 1), b2 + hstepB, voffB); PG8_STAGE(PG8_SA(0, 0), a2, voffA);
;             PG8_WAIT_V(8); PG8_WAIT_L(0); PG8_BAR; PG8_MMA(1, 0, At, B0); PG8_MMA(1, 1, At, B1); PG8_BAR; PG8_SCHED;
;             PG8_LDB(B0, 1, 0); PG8_LDB(B1, 1, 1); PG8_SCHED; PG8_LDA(At, 1, 0); PG8_STAGE(PG8_SA(0, 1), a2 + hstepA, voffA);
;             PG8_WAIT_V(8); PG8_WAIT_L(0); PG8_BAR; PG8_MMA(0, 0, At, B0); PG8_MMA(0, 1, At, B1); PG8_BAR; PG8_SCHED;
	s_setprio 1
	s_waitcnt lgkmcnt(0)
	v_mfma_f32_16x16x32_bf16 v[62:65], v[130:133], v[190:193], 0
	v_mfma_f32_16x16x32_bf16 v[58:61], v[138:141], v[190:193], 0
	v_mfma_f32_16x16x32_bf16 v[46:49], v[130:133], v[198:201], 0
	v_mfma_f32_16x16x32_bf16 v[42:45], v[138:141], v[198:201], 0
	v_mfma_f32_16x16x32_bf16 v[30:33], v[130:133], v[226:229], 0
	v_mfma_f32_16x16x32_bf16 v[26:29], v[138:141], v[226:229], 0
	v_mfma_f32_16x16x32_bf16 v[14:17], v[130:133], v[234:237], 0
	v_mfma_f32_16x16x32_bf16 v[10:13], v[138:141], v[234:237], 0
	v_mfma_f32_16x16x32_bf16 v[62:65], v[134:137], v[194:197], v[62:65]
	v_mfma_f32_16x16x32_bf16 v[58:61], v[142:145], v[194:197], v[58:61]
	v_mfma_f32_16x16x32_bf16 v[46:49], v[134:137], v[222:225], v[46:49]
	v_mfma_f32_16x16x32_bf16 v[42:45], v[142:145], v[222:225], v[42:45]
	v_mfma_f32_16x16x32_bf16 v[30:33], v[134:137], v[230:233], v[30:33]
	v_mfma_f32_16x16x32_bf16 v[26:29], v[142:145], v[230:233], v[26:29]
	v_mfma_f32_16x16x32_bf16 v[14:17], v[134:137], v[238:241], v[14:17]
	v_mfma_f32_16x16x32_bf16 v[10:13], v[142:145], v[238:241], v[10:13]
	s_setprio 0
	s_setprio 1
	v_mfma_f32_16x16x32_bf16 v[54:57], v[160:163], v[190:193], 0
	v_mfma_f32_16x16x32_bf16 v[50:53], v[182:185], v[190:193], 0
	v_mfma_f32_16x16x32_bf16 v[38:41], v[160:163], v[198:201], 0
	v_mfma_f32_16x16x32_bf16 v[34:37], v[182:185], v[198:201], 0
	v_mfma_f32_16x16x32_bf16 v[22:25], v[160:163], v[226:229], 0
	v_mfma_f32_16x16x32_bf16 v[18:21], v[182:185], v[226:229], 0
	v_mfma_f32_16x16x32_bf16 v[6:9], v[160:163], v[234:237], 0
	v_mfma_f32_16x16x32_bf16 v[2:5], v[182:185], v[234:237], 0
	v_mfma_f32_16x16x32_bf16 v[54:57], v[164:167], v[194:197], v[54:57]
	v_mfma_f32_16x16x32_bf16 v[50:53], v[186:189], v[194:197], v[50:53]
	v_mfma_f32_16x16x32_bf16 v[38:41], v[164:167], v[222:225], v[38:41]
	v_mfma_f32_16x16x32_bf16 v[34:37], v[186:189], v[222:225], v[34:37]
	v_mfma_f32_16x16x32_bf16 v[22:25], v[164:167], v[230:233], v[22:25]
	v_mfma_f32_16x16x32_bf16 v[18:21], v[186:189], v[230:233], v[18:21]
	v_mfma_f32_16x16x32_bf16 v[6:9], v[164:167], v[238:241], v[6:9]
	v_mfma_f32_16x16x32_bf16 v[2:5], v[186:189], v[238:241], v[2:5]
	s_setprio 0
	s_barrier
	s_add_i32 s49, 0, 0x18000
	s_add_i32 s88, 0, 0x1c000
	v_add_u32_e32 v142, s49, v179
	v_add_u32_e32 v186, s88, v179
	ds_read_b128 v[130:133], v142
	ds_read_b128 v[134:137], v142 offset:1024
	ds_read_b128 v[138:141], v142 offset:2048
	ds_read_b128 v[142:145], v142 offset:3072
	ds_read_b128 v[160:163], v186
	ds_read_b128 v[164:167], v186 offset:1024
	ds_read_b128 v[182:185], v186 offset:2048
	ds_read_b128 v[186:189], v186 offset:3072
	s_add_u32 s24, s24, 0x80000
	s_addc_u32 s25, s25, 0
	s_mov_b32 m0, s37
	v_lshl_add_u64 v[248:249], s[24:25], 0, v[168:169]
	ds_read_b128 v[190:193], v181 offset:32768
	ds_read_b128 v[194:197], v181 offset:33792
	ds_read_b128 v[198:201], v181 offset:34816
	ds_read_b128 v[222:225], v181 offset:35840
	ds_read_b128 v[226:229], v181 offset:36864
	ds_read_b128 v[230:233], v181 offset:37888
	ds_read_b128 v[234:237], v181 offset:38912
	ds_read_b128 v[238:241], v181 offset:39936
	global_load_lds_dwordx4 v[248:249], off
	v_lshl_add_u64 v[248:249], s[24:25], 0, v[146:147]
	s_mov_b32 m0, s38
	s_nop 0
	global_load_lds_dwordx4 v[248:249], off
	s_waitcnt vmcnt(8)
	s_waitcnt lgkmcnt(0)
	s_barrier
	s_setprio 1
	s_waitcnt lgkmcnt(0)
	v_mfma_f32_16x16x32_bf16 v[126:129], v[130:133], v[190:193], v[126:129]
	v_mfma_f32_16x16x32_bf16 v[122:125], v[138:141], v[190:193], v[122:125]
	v_mfma_f32_16x16x32_bf16 v[110:113], v[130:133], v[198:201], v[110:113]
	v_mfma_f32_16x16x32_bf16 v[106:109], v[138:141], v[198:201], v[106:109]
	v_mfma_f32_16x16x32_bf16 v[94:97], v[130:133], v[226:229], v[94:97]
	v_mfma_f32_16x16x32_bf16 v[90:93], v[138:141], v[226:229], v[90:93]
	v_mfma_f32_16x16x32_bf16 v[78:81], v[130:133], v[234:237], v[78:81]
	v_mfma_f32_16x16x32_bf16 v[74:77], v[138:141], v[234:237], v[74:77]
	v_mfma_f32_16x16x32_bf16 v[126:129], v[134:137], v[194:197], v[126:129]
	v_mfma_f32_16x16x32_bf16 v[122:125], v[142:145], v[194:197], v[122:125]
	v_mfma_f32_16x16x32_bf16 v[110:113], v[134:137], v[222:225], v[110:113]
	v_mfma_f32_16x16x32_bf16 v[106:109], v[142:145], v[222:225], v[106:109]
	v_mfma_f32_16x16x32_bf16 v[94:97], v[134:137], v[230:233], v[94:97]
	v_mfma_f32_16x16x32_bf16 v[90:93], v[142:145], v[230:233], v[90:93]
	v_mfma_f32_16x16x32_bf16 v[78:81], v[134:137], v[238:241], v[78:81]
	v_mfma_f32_16x16x32_bf16 v[74:77], v[142:145], v[238:241], v[74:77]
	s_setprio 0
	s_setprio 1
	v_mfma_f32_16x16x32_bf16 v[118:121], v[160:163], v[190:193], v[118:121]
	v_mfma_f32_16x16x32_bf16 v[114:117], v[182:185], v[190:193], v[114:117]
	v_mfma_f32_16x16x32_bf16 v[102:105], v[160:163], v[198:201], v[102:105]
	v_mfma_f32_16x16x32_bf16 v[98:101], v[182:185], v[198:201], v[98:101]
	v_mfma_f32_16x16x32_bf16 v[86:89], v[160:163], v[226:229], v[86:89]
	v_mfma_f32_16x16x32_bf16 v[82:85], v[182:185], v[226:229], v[82:85]
	v_mfma_f32_16x16x32_bf16 v[70:73], v[160:163], v[234:237], v[70:73]
	v_mfma_f32_16x16x32_bf16 v[66:69], v[182:185], v[234:237], v[66:69]
	v_mfma_f32_16x16x32_bf16 v[118:121], v[164:167], v[194:197], v[118:121]
	v_mfma_f32_16x16x32_bf16 v[114:117], v[186:189], v[194:197], v[114:117]
	v_mfma_f32_16x16x32_bf16 v[102:105], v[164:167], v[222:225], v[102:105]
	v_mfma_f32_16x16x32_bf16 v[98:101], v[186:189], v[222:225], v[98:101]
	v_mfma_f32_16x16x32_bf16 v[86:89], v[164:167], v[230:233], v[86:89]
	v_mfma_f32_16x16x32_bf16 v[82:85], v[186:189], v[230:233], v[82:85]
	v_mfma_f32_16x16x32_bf16 v[70:73], v[164:167], v[238:241], v[70:73]
	v_mfma_f32_16x16x32_bf16 v[66:69], v[186:189], v[238:241], v[66:69]
	s_setprio 0
	s_barrier
; #define PG8_STAGE(bufoff, gbase, voff) do { _Pragma("unroll") for (int _i = 0; _i < 2; ++_i) \
;         __builtin_amdgcn_global_load_lds((const unsigned*)((const char*)(gbase) + (voff)[_i]), (LAS unsigned*)(lds + (bufoff) + ldsw + _i * 8192), 16, 0, 0); } while (0)
; #define PG8_LDA(dst, b, h) do { _Pragma("unroll") for (int m = 0; m < 4; ++m) _Pragma("unroll") for (int k = 0; k < 2; ++k) dst[m][k] = *(const LAS bf16x8*)(lds + PG8_SA(b, h) + aoff + m * 2048 + k * 1024); } while (0)
; #define PG8_MMA(ai, bj, At, Bt) do { __builtin_amdgcn_s_setprio(1); _Pragma("unroll") for (int m = 0; m < 4; ++m) _Pragma("unroll") for (int n = 0; n < 2; ++n) _Pragma("unroll") for (int k = 0; k < 2; ++k) \
;         acc[ai][bj][m][n] = __builtin_amdgcn_mfma_f32_16x16x32_bf16(Bt[n][k], At[m][k], acc[ai][bj][m][n], 0, 0, 0); __builtin_amdgcn_s_setprio(0); } while (0)
; #define PG8_WAIT_V(n) asm volatile("s_waitcnt vmcnt(" #n ")" ::: "memory")
; #define PG8_WAIT_L(n) asm volatile("s_waitcnt lgkmcnt(" #n ")" ::: "memory")
; #define PG8_BAR __builtin_amdgcn_s_barrier()
; #define PG8_SCHED __builtin_amdgcn_sched_barrier(0)
; template <class Epi>
; __device__ __forceinline__ void gemm_phase(LAS unsigned char* lds, const Sched& S, const Epi& E) {
;     ...
;             PG8_LDA(At, 1, 1); PG8_STAGE(PG8_SB(1, 0), b3, voffB); PG8_STAGE(PG8_SB(1, 1), b3 + hstepB, voffB); PG8_STAGE(PG8_SA(1, 0), a3, voffA);
;             PG8_WAIT_V(8); PG8_WAIT_L(0); PG8_BAR; PG8_MMA(1, 0, At, B0); PG8_MMA(1, 1, At, B1); PG8_BAR; PG8_SCHED;
;         }
	s_add_i32 s24, s49, s34
	v_lshl_add_u64 v[176:177], v[176:177], 0, s[0:1]
	s_mov_b32 m0, s24
	ds_read_b128 v[190:193], v181 offset:49152
	ds_read_b128 v[194:197], v181 offset:50176
	ds_read_b128 v[198:201], v181 offset:51200
	ds_read_b128 v[222:225], v181 offset:52224
	ds_read_b128 v[226:229], v181 offset:53248
	ds_read_b128 v[230:233], v181 offset:54272
	ds_read_b128 v[234:237], v181 offset:55296
	ds_read_b128 v[238:241], v181 offset:56320
	global_load_lds_dwordx4 v[176:177], off
	s_add_i32 m0, s24, 0x2000
	s_add_u32 s22, s22, 0x80080
	v_lshl_add_u64 v[176:177], v[242:243], 0, s[0:1]
	s_addc_u32 s23, s23, 0
	s_add_i32 s24, s88, s34
	global_load_lds_dwordx4 v[176:177], off
	v_lshl_add_u64 v[176:177], s[22:23], 0, v[168:169]
	s_mov_b32 m0, s24
	s_nop 0
	global_load_lds_dwordx4 v[176:177], off
	v_lshl_add_u64 v[176:177], s[22:23], 0, v[146:147]
	s_add_i32 m0, s24, 0x2000
	s_nop 0
	global_load_lds_dwordx4 v[176:177], off
	v_lshl_add_u64 v[176:177], v[244:245], 0, s[0:1]
	s_mov_b32 m0, s39
	s_nop 0
	global_load_lds_dwordx4 v[176:177], off
	v_lshl_add_u64 v[176:177], v[246:247], 0, s[0:1]
	s_mov_b32 m0, s59
	s_nop 0
	global_load_lds_dwordx4 v[176:177], off
	s_waitcnt vmcnt(8)
	s_waitcnt lgkmcnt(0)
	s_barrier
	s_setprio 1
	s_waitcnt lgkmcnt(0)
	v_mfma_f32_16x16x32_bf16 v[62:65], v[130:133], v[190:193], v[62:65]
	v_mfma_f32_16x16x32_bf16 v[58:61], v[138:141], v[190:193], v[58:61]
	v_mfma_f32_16x16x32_bf16 v[46:49], v[130:133], v[198:201], v[46:49]
	v_mfma_f32_16x16x32_bf16 v[42:45], v[138:141], v[198:201], v[42:45]
	v_mfma_f32_16x16x32_bf16 v[30:33], v[130:133], v[226:229], v[30:33]
	v_mfma_f32_16x16x32_bf16 v[26:29], v[138:141], v[226:229], v[26:29]
	v_mfma_f32_16x16x32_bf16 v[14:17], v[130:133], v[234:237], v[14:17]
	v_mfma_f32_16x16x32_bf16 v[10:13], v[138:141], v[234:237], v[10:13]
	v_mfma_f32_16x16x32_bf16 v[62:65], v[134:137], v[194:197], v[62:65]
	v_mfma_f32_16x16x32_bf16 v[58:61], v[142:145], v[194:197], v[58:61]
	v_mfma_f32_16x16x32_bf16 v[46:49], v[134:137], v[222:225], v[46:49]
	v_mfma_f32_16x16x32_bf16 v[42:45], v[142:145], v[222:225], v[42:45]
	v_mfma_f32_16x16x32_bf16 v[30:33], v[134:137], v[230:233], v[30:33]
	v_mfma_f32_16x16x32_bf16 v[26:29], v[142:145], v[230:233], v[26:29]
	v_mfma_f32_16x16x32_bf16 v[14:17], v[134:137], v[238:241], v[14:17]
	v_mfma_f32_16x16x32_bf16 v[10:13], v[142:145], v[238:241], v[10:13]
	s_setprio 0
	s_setprio 1
	v_mfma_f32_16x16x32_bf16 v[54:57], v[160:163], v[190:193], v[54:57]
	v_mfma_f32_16x16x32_bf16 v[50:53], v[182:185], v[190:193], v[50:53]
	v_mfma_f32_16x16x32_bf16 v[38:41], v[160:163], v[198:201], v[38:41]
	v_mfma_f32_16x16x32_bf16 v[34:37], v[182:185], v[198:201], v[34:37]
	v_mfma_f32_16x16x32_bf16 v[22:25], v[160:163], v[226:229], v[22:25]
	v_mfma_f32_16x16x32_bf16 v[18:21], v[182:185], v[226:229], v[18:21]
	v_mfma_f32_16x16x32_bf16 v[6:9], v[160:163], v[234:237], v[6:9]
	v_mfma_f32_16x16x32_bf16 v[2:5], v[182:185], v[234:237], v[2:5]
	v_mfma_f32_16x16x32_bf16 v[54:57], v[164:167], v[194:197], v[54:57]
	v_mfma_f32_16x16x32_bf16 v[50:53], v[186:189], v[194:197], v[50:53]
	v_mfma_f32_16x16x32_bf16 v[38:41], v[164:167], v[222:225], v[38:41]
	v_mfma_f32_16x16x32_bf16 v[34:37], v[186:189], v[222:225], v[34:37]
	v_mfma_f32_16x16x32_bf16 v[22:25], v[164:167], v[230:233], v[22:25]
	v_mfma_f32_16x16x32_bf16 v[18:21], v[186:189], v[230:233], v[18:21]
	v_mfma_f32_16x16x32_bf16 v[6:9], v[164:167], v[238:241], v[6:9]
	v_mfma_f32_16x16x32_bf16 v[2:5], v[186:189], v[238:241], v[2:5]
	s_setprio 0
	s_barrier
	s_add_u32 s20, s20, 0x100
	s_addc_u32 s21, s21, 0
	s_add_u32 s82, s82, 0x100
	s_addc_u32 s94, s94, 0
	s_cmp_ge_i32 s95, s19
	s_mov_b32 s22, s95
	s_cbranch_scc1 .Lpeel_exit_wo

; #define PG8_STAGE(bufoff, gbase, voff) do { _Pragma("unroll") for (int _i = 0; _i < 2; ++_i) \
;         __builtin_amdgcn_global_load_lds((const unsigned*)((const char*)(gbase) + (voff)[_i]), (LAS unsigned*)(lds + (bufoff) + ldsw + _i * 8192), 16, 0, 0); } while (0)
; #define PG8_LDA(dst, b, h) do { _Pragma("unroll") for (int m = 0; m < 4; ++m) _Pragma("unroll") for (int k = 0; k < 2; ++k) dst[m][k] = *(const LAS bf16x8*)(lds + PG8_SA(b, h) + aoff + m * 2048 + k * 1024); } while (0)
; #define PG8_LDB(dst, b, h) do { _Pragma("unroll") for (int n = 0; n < 2; ++n) _Pragma("unroll") for (int k = 0; k < 2; ++k) dst[n][k] = *(const LAS bf16x8*)(lds + PG8_SB(b, h) + boff + n * 2048 + k * 1024); } while (0)
; #define PG8_MMA(ai, bj, At, Bt) do { __builtin_amdgcn_s_setprio(1); _Pragma("unroll") for (int m = 0; m < 4; ++m) _Pragma("unroll") for (int n = 0; n < 2; ++n) _Pragma("unroll") for (int k = 0; k < 2; ++k) \
;         acc[ai][bj][m][n] = __builtin_amdgcn_mfma_f32_16x16x32_bf16(Bt[n][k], At[m][k], acc[ai][bj][m][n], 0, 0, 0); __builtin_amdgcn_s_setprio(0); } while (0)
; #define PG8_WAIT_V(n) asm volatile("s_waitcnt vmcnt(" #n ")" ::: "memory")
; #define PG8_WAIT_L(n) asm volatile("s_waitcnt lgkmcnt(" #n ")" ::: "memory")
; #define PG8_BAR __builtin_amdgcn_s_barrier()
; #define PG8_SCHED __builtin_amdgcn_sched_barrier(0)
; template <class Epi>
; __device__ __forceinline__ void gemm_phase(LAS unsigned char* lds, const Sched& S, const Epi& E) {
;     ...
;             const bool last = (t == nt - 2);
;             const char* a1 = cA + (size_t)(t + 1) * kstep;
;             const char* a2 = last ? nA : cA + (size_t)(t + 2) * kstep; const char* b2 = last ? nB : cB + (size_t)(t + 2) * kstep;
;             const char* a3 = a2 + kstep; const char* b3 = b2 + kstep;
;             PG8_LDB(B0, 0, 0); PG8_LDB(B1, 0, 1); PG8_SCHED; PG8_LDA(At, 0, 0); PG8_STAGE(PG8_SA(1, 1), a1 + hstepA, voffA);
;             PG8_WAIT_V(8); PG8_WAIT_L(0); PG8_BAR; PG8_MMA(0, 0, At, B0); PG8_MMA(0, 1, At, B1); PG8_BAR; PG8_SCHED;
.LBB0_2099:
	s_and_b64 s[30:31], s[22:23], exec
	s_cselect_b32 s5, s19, s27
	s_cselect_b32 s15, s18, s26
	s_cselect_b32 s17, s21, s29
	s_cselect_b32 s34, s20, s28
	s_add_u32 s26, s26, 0x80080
	s_addc_u32 s27, s27, 0
	s_add_u32 s35, s28, 0x100
	v_mov_b32_e32 v2, 0
	s_addc_u32 s36, s29, 0
	s_mov_b32 s37, -2
	s_waitcnt lgkmcnt(0)
	s_add_u32 s28, s26, 0xfff80080
	s_addc_u32 s29, s27, -1
	s_add_i32 s49, 0, 0x10000
	s_cmp_eq_u32 s37, 4
	s_cselect_b32 s31, s5, s29
	s_cselect_b32 s30, s15, s28
	s_cselect_b32 s29, s17, s36
	s_cselect_b32 s28, s34, s35
	s_add_i32 s88, 0, 0x14000
	v_add_u32_e32 v106, s49, v197
	v_add_u32_e32 v158, s88, v197
	ds_read_b128 v[90:93], v106
	ds_read_b128 v[94:97], v106 offset:1024
	ds_read_b128 v[102:105], v106 offset:2048
	ds_read_b128 v[106:109], v106 offset:3072
	ds_read_b128 v[146:149], v158
	ds_read_b128 v[150:153], v158 offset:1024
	ds_read_b128 v[154:157], v158 offset:2048
	ds_read_b128 v[158:161], v158 offset:3072
	v_lshl_add_u64 v[200:201], s[26:27], 0, v[184:185]
	s_add_i32 m0, s64, 0xc000
	ds_read_b128 v[188:191], v199
	ds_read_b128 v[192:195], v199 offset:1024
	ds_read_b128 v[222:225], v199 offset:2048
	ds_read_b128 v[226:229], v199 offset:3072
	ds_read_b128 v[230:233], v199 offset:4096
	ds_read_b128 v[234:237], v199 offset:5120
	ds_read_b128 v[238:241], v199 offset:6144
	ds_read_b128 v[242:245], v199 offset:7168
	global_load_lds_dwordx4 v[200:201], off
	v_lshl_add_u64 v[200:201], s[26:27], 0, v[186:187]
	s_add_i32 m0, s64, 0xe000
	s_nop 0
	global_load_lds_dwordx4 v[200:201], off
	s_waitcnt vmcnt(8)
	s_waitcnt lgkmcnt(0)
	s_barrier
	s_setprio 1
	s_waitcnt lgkmcnt(0)
	v_mfma_f32_16x16x32_bf16 v[142:145], v[90:93], v[188:191], 0
	v_mfma_f32_16x16x32_bf16 v[138:141], v[102:105], v[188:191], 0
	v_mfma_f32_16x16x32_bf16 v[126:129], v[90:93], v[222:225], 0
	v_mfma_f32_16x16x32_bf16 v[122:125], v[102:105], v[222:225], 0
	v_mfma_f32_16x16x32_bf16 v[110:113], v[90:93], v[230:233], 0
	v_mfma_f32_16x16x32_bf16 v[98:101], v[102:105], v[230:233], 0
	v_mfma_f32_16x16x32_bf16 v[78:81], v[90:93], v[238:241], 0
	v_mfma_f32_16x16x32_bf16 v[74:77], v[102:105], v[238:241], 0
	v_mfma_f32_16x16x32_bf16 v[142:145], v[94:97], v[192:195], v[142:145]
	v_mfma_f32_16x16x32_bf16 v[138:141], v[106:109], v[192:195], v[138:141]
	v_mfma_f32_16x16x32_bf16 v[126:129], v[94:97], v[226:229], v[126:129]
	v_mfma_f32_16x16x32_bf16 v[122:125], v[106:109], v[226:229], v[122:125]
	v_mfma_f32_16x16x32_bf16 v[110:113], v[94:97], v[234:237], v[110:113]
	v_mfma_f32_16x16x32_bf16 v[98:101], v[106:109], v[234:237], v[98:101]
	v_mfma_f32_16x16x32_bf16 v[78:81], v[94:97], v[242:245], v[78:81]
	v_mfma_f32_16x16x32_bf16 v[74:77], v[106:109], v[242:245], v[74:77]
	s_setprio 0
	s_setprio 1
	v_mfma_f32_16x16x32_bf16 v[134:137], v[146:149], v[188:191], 0
	v_mfma_f32_16x16x32_bf16 v[130:133], v[154:157], v[188:191], 0
	v_mfma_f32_16x16x32_bf16 v[118:121], v[146:149], v[222:225], 0
	v_mfma_f32_16x16x32_bf16 v[114:117], v[154:157], v[222:225], 0
	v_mfma_f32_16x16x32_bf16 v[86:89], v[146:149], v[230:233], 0
	v_mfma_f32_16x16x32_bf16 v[82:85], v[154:157], v[230:233], 0
	v_mfma_f32_16x16x32_bf16 v[70:73], v[146:149], v[238:241], 0
	v_mfma_f32_16x16x32_bf16 v[66:69], v[154:157], v[238:241], 0
	v_mfma_f32_16x16x32_bf16 v[134:137], v[150:153], v[192:195], v[134:137]
	v_mfma_f32_16x16x32_bf16 v[130:133], v[158:161], v[192:195], v[130:133]
	v_mfma_f32_16x16x32_bf16 v[118:121], v[150:153], v[226:229], v[118:121]
	v_mfma_f32_16x16x32_bf16 v[114:117], v[158:161], v[226:229], v[114:117]
	v_mfma_f32_16x16x32_bf16 v[86:89], v[150:153], v[234:237], v[86:89]
	v_mfma_f32_16x16x32_bf16 v[82:85], v[158:161], v[234:237], v[82:85]
	v_mfma_f32_16x16x32_bf16 v[70:73], v[150:153], v[242:245], v[70:73]
	v_mfma_f32_16x16x32_bf16 v[66:69], v[158:161], v[242:245], v[66:69]
	s_setprio 0
	s_barrier
	s_add_i32 s49, s49, s25
	v_lshl_add_u64 v[200:201], s[28:29], 0, v[168:169]
	s_mov_b32 m0, s49
	ds_read_b128 v[188:191], v199 offset:16384
	ds_read_b128 v[192:195], v199 offset:17408
	ds_read_b128 v[222:225], v199 offset:18432
	ds_read_b128 v[226:229], v199 offset:19456
	ds_read_b128 v[230:233], v199 offset:20480
	ds_read_b128 v[234:237], v199 offset:21504
	ds_read_b128 v[238:241], v199 offset:22528
	ds_read_b128 v[242:245], v199 offset:23552
	global_load_lds_dwordx4 v[200:201], off
	s_add_i32 m0, s49, 0x2000
	s_add_u32 s96, s28, 0x20000
	v_lshl_add_u64 v[246:247], s[28:29], 0, v[166:167]
	s_addc_u32 s97, s29, 0
	s_add_i32 s49, s88, s25
	global_load_lds_dwordx4 v[246:247], off
	v_lshl_add_u64 v[248:249], s[96:97], 0, v[168:169]
	s_mov_b32 m0, s49
	v_lshl_add_u64 v[250:251], s[30:31], 0, v[164:165]
	global_load_lds_dwordx4 v[248:249], off
	v_lshl_add_u64 v[248:249], s[96:97], 0, v[166:167]
	s_add_i32 m0, s49, 0x2000
	s_nop 0
	global_load_lds_dwordx4 v[248:249], off
	v_lshl_add_u64 v[248:249], s[30:31], 0, v[162:163]
	s_mov_b32 m0, s64
	s_nop 0
	global_load_lds_dwordx4 v[248:249], off
	s_mov_b32 m0, s65
	s_nop 0
	global_load_lds_dwordx4 v[250:251], off
	s_waitcnt vmcnt(8)
	s_waitcnt lgkmcnt(0)
	s_barrier
; #define PG8_STAGE(bufoff, gbase, voff) do { _Pragma("unroll") for (int _i = 0; _i < 2; ++_i) \
;         __builtin_amdgcn_global_load_lds((const unsigned*)((const char*)(gbase) + (voff)[_i]), (LAS unsigned*)(lds + (bufoff) + ldsw + _i * 8192), 16, 0, 0); } while (0)
; #define PG8_LDA(dst, b, h) do { _Pragma("unroll") for (int m = 0; m < 4; ++m) _Pragma("unroll") for (int k = 0; k < 2; ++k) dst[m][k] = *(const LAS bf16x8*)(lds + PG8_SA(b, h) + aoff + m * 2048 + k * 1024); } while (0)
; #define PG8_LDB(dst, b, h) do { _Pragma("unroll") for (int n = 0; n < 2; ++n) _Pragma("unroll") for (int k = 0; k < 2; ++k) dst[n][k] = *(const LAS bf16x8*)(lds + PG8_SB(b, h) + boff + n * 2048 + k * 1024); } while (0)
; #define PG8_MMA(ai, bj, At, Bt) do { __builtin_amdgcn_s_setprio(1); _Pragma("unroll") for (int m = 0; m < 4; ++m) _Pragma("unroll") for (int n = 0; n < 2; ++n) _Pragma("unroll") for (int k = 0; k < 2; ++k) \
;         acc[ai][bj][m][n] = __builtin_amdgcn_mfma_f32_16x16x32_bf16(Bt[n][k], At[m][k], acc[ai][bj][m][n], 0, 0, 0); __builtin_amdgcn_s_setprio(0); } while (0)
; #define PG8_WAIT_V(n) asm volatile("s_waitcnt vmcnt(" #n ")" ::: "memory")
; #define PG8_WAIT_L(n) asm volatile("s_waitcnt lgkmcnt(" #n ")" ::: "memory")
; #define PG8_BAR __builtin_amdgcn_s_barrier()
; #define PG8_SCHED __builtin_amdgcn_sched_barrier(0)
; template <class Epi>
; __device__ __forceinline__ void gemm_phase(LAS unsigned char* lds, const Sched& S, const Epi& E) {
;     ...
;             PG8_LDA(At, 0, 1); PG8_STAGE(PG8_SB(0, 0), b2, voffB); PG8_STAGE(PG8_SB(0, 1), b2 + hstepB, voffB); PG8_STAGE(PG8_SA(0, 0), a2, voffA);
;             PG8_WAIT_V(8); PG8_WAIT_L(0); PG8_BAR; PG8_MMA(1, 0, At, B0); PG8_MMA(1, 1, At, B1); PG8_BAR; PG8_SCHED;
;             PG8_LDB(B0, 1, 0); PG8_LDB(B1, 1, 1); PG8_SCHED; PG8_LDA(At, 1, 0); PG8_STAGE(PG8_SA(0, 1), a2 + hstepA, voffA);
;             PG8_WAIT_V(8); PG8_WAIT_L(0); PG8_BAR; PG8_MMA(0, 0, At, B0); PG8_MMA(0, 1, At, B1); PG8_BAR; PG8_SCHED;
	s_setprio 1
	s_waitcnt lgkmcnt(0)
	v_mfma_f32_16x16x32_bf16 v[62:65], v[90:93], v[188:191], 0
	v_mfma_f32_16x16x32_bf16 v[58:61], v[102:105], v[188:191], 0
	v_mfma_f32_16x16x32_bf16 v[46:49], v[90:93], v[222:225], 0
	v_mfma_f32_16x16x32_bf16 v[42:45], v[102:105], v[222:225], 0
	v_mfma_f32_16x16x32_bf16 v[30:33], v[90:93], v[230:233], 0
	v_mfma_f32_16x16x32_bf16 v[26:29], v[102:105], v[230:233], 0
	v_mfma_f32_16x16x32_bf16 v[14:17], v[90:93], v[238:241], 0
	v_mfma_f32_16x16x32_bf16 v[10:13], v[102:105], v[238:241], 0
	v_mfma_f32_16x16x32_bf16 v[62:65], v[94:97], v[192:195], v[62:65]
	v_mfma_f32_16x16x32_bf16 v[58:61], v[106:109], v[192:195], v[58:61]
	v_mfma_f32_16x16x32_bf16 v[46:49], v[94:97], v[226:229], v[46:49]
	v_mfma_f32_16x16x32_bf16 v[42:45], v[106:109], v[226:229], v[42:45]
	v_mfma_f32_16x16x32_bf16 v[30:33], v[94:97], v[234:237], v[30:33]
	v_mfma_f32_16x16x32_bf16 v[26:29], v[106:109], v[234:237], v[26:29]
	v_mfma_f32_16x16x32_bf16 v[14:17], v[94:97], v[242:245], v[14:17]
	v_mfma_f32_16x16x32_bf16 v[10:13], v[106:109], v[242:245], v[10:13]
	s_setprio 0
	s_setprio 1
	v_mfma_f32_16x16x32_bf16 v[54:57], v[146:149], v[188:191], 0
	v_mfma_f32_16x16x32_bf16 v[50:53], v[154:157], v[188:191], 0
	v_mfma_f32_16x16x32_bf16 v[38:41], v[146:149], v[222:225], 0
	v_mfma_f32_16x16x32_bf16 v[34:37], v[154:157], v[222:225], 0
	v_mfma_f32_16x16x32_bf16 v[22:25], v[146:149], v[230:233], 0
	v_mfma_f32_16x16x32_bf16 v[18:21], v[154:157], v[230:233], 0
	v_mfma_f32_16x16x32_bf16 v[6:9], v[146:149], v[238:241], 0
	v_mfma_f32_16x16x32_bf16 v[2:5], v[154:157], v[238:241], 0
	v_mfma_f32_16x16x32_bf16 v[54:57], v[150:153], v[192:195], v[54:57]
	v_mfma_f32_16x16x32_bf16 v[50:53], v[158:161], v[192:195], v[50:53]
	v_mfma_f32_16x16x32_bf16 v[38:41], v[150:153], v[226:229], v[38:41]
	v_mfma_f32_16x16x32_bf16 v[34:37], v[158:161], v[226:229], v[34:37]
	v_mfma_f32_16x16x32_bf16 v[22:25], v[150:153], v[234:237], v[22:25]
	v_mfma_f32_16x16x32_bf16 v[18:21], v[158:161], v[234:237], v[18:21]
	v_mfma_f32_16x16x32_bf16 v[6:9], v[150:153], v[242:245], v[6:9]
	v_mfma_f32_16x16x32_bf16 v[2:5], v[158:161], v[242:245], v[2:5]
	s_setprio 0
	s_barrier
	s_add_i32 s49, 0, 0x18000
	s_add_i32 s88, 0, 0x1c000
	v_add_u32_e32 v106, s49, v197
	v_add_u32_e32 v158, s88, v197
	ds_read_b128 v[90:93], v106
	ds_read_b128 v[94:97], v106 offset:1024
	ds_read_b128 v[102:105], v106 offset:2048
	ds_read_b128 v[106:109], v106 offset:3072
	ds_read_b128 v[146:149], v158
	ds_read_b128 v[150:153], v158 offset:1024
	ds_read_b128 v[154:157], v158 offset:2048
	ds_read_b128 v[158:161], v158 offset:3072
	s_add_u32 s30, s30, 0x80000
	s_addc_u32 s31, s31, 0
	s_mov_b32 m0, s66
	v_lshl_add_u64 v[252:253], s[30:31], 0, v[162:163]
	ds_read_b128 v[188:191], v199 offset:32768
	ds_read_b128 v[192:195], v199 offset:33792
	ds_read_b128 v[222:225], v199 offset:34816
	ds_read_b128 v[226:229], v199 offset:35840
	ds_read_b128 v[230:233], v199 offset:36864
	ds_read_b128 v[234:237], v199 offset:37888
	ds_read_b128 v[238:241], v199 offset:38912
	ds_read_b128 v[242:245], v199 offset:39936
	global_load_lds_dwordx4 v[252:253], off
	v_lshl_add_u64 v[252:253], s[30:31], 0, v[164:165]
	s_mov_b32 m0, s67
	s_nop 0
	global_load_lds_dwordx4 v[252:253], off
	s_waitcnt vmcnt(8)
	s_waitcnt lgkmcnt(0)
	s_barrier
	s_setprio 1
	s_waitcnt lgkmcnt(0)
	v_mfma_f32_16x16x32_bf16 v[142:145], v[90:93], v[188:191], v[142:145]
	v_mfma_f32_16x16x32_bf16 v[138:141], v[102:105], v[188:191], v[138:141]
	v_mfma_f32_16x16x32_bf16 v[126:129], v[90:93], v[222:225], v[126:129]
	v_mfma_f32_16x16x32_bf16 v[122:125], v[102:105], v[222:225], v[122:125]
	v_mfma_f32_16x16x32_bf16 v[110:113], v[90:93], v[230:233], v[110:113]
	v_mfma_f32_16x16x32_bf16 v[98:101], v[102:105], v[230:233], v[98:101]
	v_mfma_f32_16x16x32_bf16 v[78:81], v[90:93], v[238:241], v[78:81]
	v_mfma_f32_16x16x32_bf16 v[74:77], v[102:105], v[238:241], v[74:77]
	v_mfma_f32_16x16x32_bf16 v[142:145], v[94:97], v[192:195], v[142:145]
	v_mfma_f32_16x16x32_bf16 v[138:141], v[106:109], v[192:195], v[138:141]
	v_mfma_f32_16x16x32_bf16 v[126:129], v[94:97], v[226:229], v[126:129]
	v_mfma_f32_16x16x32_bf16 v[122:125], v[106:109], v[226:229], v[122:125]
	v_mfma_f32_16x16x32_bf16 v[110:113], v[94:97], v[234:237], v[110:113]
	v_mfma_f32_16x16x32_bf16 v[98:101], v[106:109], v[234:237], v[98:101]
	v_mfma_f32_16x16x32_bf16 v[78:81], v[94:97], v[242:245], v[78:81]
	v_mfma_f32_16x16x32_bf16 v[74:77], v[106:109], v[242:245], v[74:77]
	s_setprio 0
	s_setprio 1
	v_mfma_f32_16x16x32_bf16 v[134:137], v[146:149], v[188:191], v[134:137]
	v_mfma_f32_16x16x32_bf16 v[130:133], v[154:157], v[188:191], v[130:133]
	v_mfma_f32_16x16x32_bf16 v[118:121], v[146:149], v[222:225], v[118:121]
	v_mfma_f32_16x16x32_bf16 v[114:117], v[154:157], v[222:225], v[114:117]
	v_mfma_f32_16x16x32_bf16 v[86:89], v[146:149], v[230:233], v[86:89]
	v_mfma_f32_16x16x32_bf16 v[82:85], v[154:157], v[230:233], v[82:85]
	v_mfma_f32_16x16x32_bf16 v[70:73], v[146:149], v[238:241], v[70:73]
	v_mfma_f32_16x16x32_bf16 v[66:69], v[154:157], v[238:241], v[66:69]
	v_mfma_f32_16x16x32_bf16 v[134:137], v[150:153], v[192:195], v[134:137]
	v_mfma_f32_16x16x32_bf16 v[130:133], v[158:161], v[192:195], v[130:133]
	v_mfma_f32_16x16x32_bf16 v[118:121], v[150:153], v[226:229], v[118:121]
	v_mfma_f32_16x16x32_bf16 v[114:117], v[158:161], v[226:229], v[114:117]
	v_mfma_f32_16x16x32_bf16 v[86:89], v[150:153], v[234:237], v[86:89]
	v_mfma_f32_16x16x32_bf16 v[82:85], v[158:161], v[234:237], v[82:85]
	v_mfma_f32_16x16x32_bf16 v[70:73], v[150:153], v[242:245], v[70:73]
	v_mfma_f32_16x16x32_bf16 v[66:69], v[158:161], v[242:245], v[66:69]
	s_setprio 0
	s_barrier
; #define PG8_STAGE(bufoff, gbase, voff) do { _Pragma("unroll") for (int _i = 0; _i < 2; ++_i) \
;         __builtin_amdgcn_global_load_lds((const unsigned*)((const char*)(gbase) + (voff)[_i]), (LAS unsigned*)(lds + (bufoff) + ldsw + _i * 8192), 16, 0, 0); } while (0)
; #define PG8_LDA(dst, b, h) do { _Pragma("unroll") for (int m = 0; m < 4; ++m) _Pragma("unroll") for (int k = 0; k < 2; ++k) dst[m][k] = *(const LAS bf16x8*)(lds + PG8_SA(b, h) + aoff + m * 2048 + k * 1024); } while (0)
; #define PG8_MMA(ai, bj, At, Bt) do { __builtin_amdgcn_s_setprio(1); _Pragma("unroll") for (int m = 0; m < 4; ++m) _Pragma("unroll") for (int n = 0; n < 2; ++n) _Pragma("unroll") for (int k = 0; k < 2; ++k) \
;         acc[ai][bj][m][n] = __builtin_amdgcn_mfma_f32_16x16x32_bf16(Bt[n][k], At[m][k], acc[ai][bj][m][n], 0, 0, 0); __builtin_amdgcn_s_setprio(0); } while (0)
; #define PG8_WAIT_V(n) asm volatile("s_waitcnt vmcnt(" #n ")" ::: "memory")
; #define PG8_WAIT_L(n) asm volatile("s_waitcnt lgkmcnt(" #n ")" ::: "memory")
; #define PG8_BAR __builtin_amdgcn_s_barrier()
; #define PG8_SCHED __builtin_amdgcn_sched_barrier(0)
; template <class Epi>
; __device__ __forceinline__ void gemm_phase(LAS unsigned char* lds, const Sched& S, const Epi& E) {
;     ...
;             PG8_LDA(At, 1, 1); PG8_STAGE(PG8_SB(1, 0), b3, voffB); PG8_STAGE(PG8_SB(1, 1), b3 + hstepB, voffB); PG8_STAGE(PG8_SA(1, 0), a3, voffA);
;             PG8_WAIT_V(8); PG8_WAIT_L(0); PG8_BAR; PG8_MMA(1, 0, At, B0); PG8_MMA(1, 1, At, B1); PG8_BAR; PG8_SCHED;
;         }
	s_add_i32 s30, s49, s25
	v_lshl_add_u64 v[200:201], v[200:201], 0, s[0:1]
	s_mov_b32 m0, s30
	ds_read_b128 v[188:191], v199 offset:49152
	ds_read_b128 v[192:195], v199 offset:50176
	ds_read_b128 v[222:225], v199 offset:51200
	ds_read_b128 v[226:229], v199 offset:52224
	ds_read_b128 v[230:233], v199 offset:53248
	ds_read_b128 v[234:237], v199 offset:54272
	ds_read_b128 v[238:241], v199 offset:55296
	ds_read_b128 v[242:245], v199 offset:56320
	global_load_lds_dwordx4 v[200:201], off
	s_add_i32 m0, s30, 0x2000
	s_add_u32 s28, s28, 0x20080
	v_lshl_add_u64 v[200:201], v[246:247], 0, s[0:1]
	s_addc_u32 s29, s29, 0
	s_add_i32 s30, s88, s25
	global_load_lds_dwordx4 v[200:201], off
	v_lshl_add_u64 v[200:201], s[28:29], 0, v[168:169]
	s_mov_b32 m0, s30
	s_nop 0
	global_load_lds_dwordx4 v[200:201], off
	v_lshl_add_u64 v[200:201], s[28:29], 0, v[166:167]
	s_add_i32 m0, s30, 0x2000
	s_nop 0
	global_load_lds_dwordx4 v[200:201], off
	v_lshl_add_u64 v[200:201], v[248:249], 0, s[0:1]
	s_mov_b32 m0, s68
	s_nop 0
	global_load_lds_dwordx4 v[200:201], off
	v_lshl_add_u64 v[200:201], v[250:251], 0, s[0:1]
	s_mov_b32 m0, s69
	s_nop 0
	global_load_lds_dwordx4 v[200:201], off
	s_waitcnt vmcnt(8)
	s_waitcnt lgkmcnt(0)
	s_barrier
	s_setprio 1
	s_waitcnt lgkmcnt(0)
	v_mfma_f32_16x16x32_bf16 v[62:65], v[90:93], v[188:191], v[62:65]
	v_mfma_f32_16x16x32_bf16 v[58:61], v[102:105], v[188:191], v[58:61]
	v_mfma_f32_16x16x32_bf16 v[46:49], v[90:93], v[222:225], v[46:49]
	v_mfma_f32_16x16x32_bf16 v[42:45], v[102:105], v[222:225], v[42:45]
	v_mfma_f32_16x16x32_bf16 v[30:33], v[90:93], v[230:233], v[30:33]
	v_mfma_f32_16x16x32_bf16 v[26:29], v[102:105], v[230:233], v[26:29]
	v_mfma_f32_16x16x32_bf16 v[14:17], v[90:93], v[238:241], v[14:17]
	v_mfma_f32_16x16x32_bf16 v[10:13], v[102:105], v[238:241], v[10:13]
	v_mfma_f32_16x16x32_bf16 v[62:65], v[94:97], v[192:195], v[62:65]
	v_mfma_f32_16x16x32_bf16 v[58:61], v[106:109], v[192:195], v[58:61]
	v_mfma_f32_16x16x32_bf16 v[46:49], v[94:97], v[226:229], v[46:49]
	v_mfma_f32_16x16x32_bf16 v[42:45], v[106:109], v[226:229], v[42:45]
	v_mfma_f32_16x16x32_bf16 v[30:33], v[94:97], v[234:237], v[30:33]
	v_mfma_f32_16x16x32_bf16 v[26:29], v[106:109], v[234:237], v[26:29]
	v_mfma_f32_16x16x32_bf16 v[14:17], v[94:97], v[242:245], v[14:17]
	v_mfma_f32_16x16x32_bf16 v[10:13], v[106:109], v[242:245], v[10:13]
	s_setprio 0
	s_setprio 1
	v_mfma_f32_16x16x32_bf16 v[54:57], v[146:149], v[188:191], v[54:57]
	v_mfma_f32_16x16x32_bf16 v[50:53], v[154:157], v[188:191], v[50:53]
	v_mfma_f32_16x16x32_bf16 v[38:41], v[146:149], v[222:225], v[38:41]
	v_mfma_f32_16x16x32_bf16 v[34:37], v[154:157], v[222:225], v[34:37]
	v_mfma_f32_16x16x32_bf16 v[22:25], v[146:149], v[230:233], v[22:25]
	v_mfma_f32_16x16x32_bf16 v[18:21], v[154:157], v[230:233], v[18:21]
	v_mfma_f32_16x16x32_bf16 v[6:9], v[146:149], v[238:241], v[6:9]
	v_mfma_f32_16x16x32_bf16 v[2:5], v[154:157], v[238:241], v[2:5]
	v_mfma_f32_16x16x32_bf16 v[54:57], v[150:153], v[192:195], v[54:57]
	v_mfma_f32_16x16x32_bf16 v[50:53], v[158:161], v[192:195], v[50:53]
	v_mfma_f32_16x16x32_bf16 v[38:41], v[150:153], v[226:229], v[38:41]
	v_mfma_f32_16x16x32_bf16 v[34:37], v[158:161], v[226:229], v[34:37]
	v_mfma_f32_16x16x32_bf16 v[22:25], v[150:153], v[234:237], v[22:25]
	v_mfma_f32_16x16x32_bf16 v[18:21], v[158:161], v[234:237], v[18:21]
	v_mfma_f32_16x16x32_bf16 v[6:9], v[150:153], v[242:245], v[6:9]
	v_mfma_f32_16x16x32_bf16 v[2:5], v[158:161], v[242:245], v[2:5]
	s_setprio 0
	s_barrier
	s_add_i32 s37, s37, 2
	s_add_u32 s26, s26, 0x100
	s_addc_u32 s27, s27, 0
	s_add_u32 s35, s35, 0x100
	s_addc_u32 s36, s36, 0
	s_cmp_gt_u32 s37, 5
	s_cbranch_scc1 .Lpeel_exit_pool

; #define PG8_BAR __builtin_amdgcn_s_barrier()
; template <class Epi>
; __device__ __forceinline__ void gemm_phase(LAS unsigned char* lds, const Sched& S, const Epi& E) {
;     ...
;         if (wr == 0) PG8_BAR;
.Lpeel_exit_pool:
	s_and_b64 vcc, exec, s[12:13]
	s_cbranch_vccz .LBB0_2103
	s_barrier

; #define PG8_STAGE(bufoff, gbase, voff) do { _Pragma("unroll") for (int _i = 0; _i < 2; ++_i) \
;         __builtin_amdgcn_global_load_lds((const unsigned*)((const char*)(gbase) + (voff)[_i]), (LAS unsigned*)(lds + (bufoff) + ldsw + _i * 8192), 16, 0, 0); } while (0)
; #define PG8_LDA(dst, b, h) do { _Pragma("unroll") for (int m = 0; m < 4; ++m) _Pragma("unroll") for (int k = 0; k < 2; ++k) dst[m][k] = *(const LAS bf16x8*)(lds + PG8_SA(b, h) + aoff + m * 2048 + k * 1024); } while (0)
; #define PG8_LDB(dst, b, h) do { _Pragma("unroll") for (int n = 0; n < 2; ++n) _Pragma("unroll") for (int k = 0; k < 2; ++k) dst[n][k] = *(const LAS bf16x8*)(lds + PG8_SB(b, h) + boff + n * 2048 + k * 1024); } while (0)
; #define PG8_MMA(ai, bj, At, Bt) do { __builtin_amdgcn_s_setprio(1); _Pragma("unroll") for (int m = 0; m < 4; ++m) _Pragma("unroll") for (int n = 0; n < 2; ++n) _Pragma("unroll") for (int k = 0; k < 2; ++k) \
;         acc[ai][bj][m][n] = __builtin_amdgcn_mfma_f32_16x16x32_bf16(Bt[n][k], At[m][k], acc[ai][bj][m][n], 0, 0, 0); __builtin_amdgcn_s_setprio(0); } while (0)
; #define PG8_WAIT_V(n) asm volatile("s_waitcnt vmcnt(" #n ")" ::: "memory")
; #define PG8_WAIT_L(n) asm volatile("s_waitcnt lgkmcnt(" #n ")" ::: "memory")
; #define PG8_BAR __builtin_amdgcn_s_barrier()
; #define PG8_SCHED __builtin_amdgcn_sched_barrier(0)
; template <class Epi>
; __device__ __forceinline__ void gemm_phase(LAS unsigned char* lds, const Sched& S, const Epi& E) {
;     ...
;             const bool last = (t == nt - 2);
;             const char* a1 = cA + (size_t)(t + 1) * kstep;
;             const char* a2 = last ? nA : cA + (size_t)(t + 2) * kstep; const char* b2 = last ? nB : cB + (size_t)(t + 2) * kstep;
;             const char* a3 = a2 + kstep; const char* b3 = b2 + kstep;
;             PG8_LDB(B0, 0, 0); PG8_LDB(B1, 0, 1); PG8_SCHED; PG8_LDA(At, 0, 0); PG8_STAGE(PG8_SA(1, 1), a1 + hstepA, voffA);
;             PG8_WAIT_V(8); PG8_WAIT_L(0); PG8_BAR; PG8_MMA(0, 0, At, B0); PG8_MMA(0, 1, At, B1); PG8_BAR; PG8_SCHED;
.LBB0_2277:
	s_add_u32 s24, s24, 0x80080
	s_addc_u32 s25, s25, 0
	s_add_u32 s9, s26, 0x100
	v_mov_b32_e32 v2, 0
	s_addc_u32 s11, s27, 0
	s_mov_b32 s69, -2
	s_add_u32 s26, s24, 0xfff80080
	s_addc_u32 s27, s25, -1
	s_add_i32 s49, 0, 0x10000
	s_cmp_eq_u32 s69, 28
	s_cselect_b32 s29, s19, s27
	s_cselect_b32 s28, s18, s26
	v_add_u32_e32 v157, s49, v153
	s_cselect_b32 s27, s23, s11
	s_cselect_b32 s26, s22, s9
	s_add_i32 s82, 0, 0x14000
	ds_read_b128 v[140:143], v157
	ds_read_b128 v[144:147], v157 offset:1024
	ds_read_b128 v[148:151], v157 offset:2048
	ds_read_b128 v[158:161], v157 offset:3072
	v_add_u32_e32 v157, s82, v153
	ds_read_b128 v[162:165], v157
	ds_read_b128 v[176:179], v157 offset:1024
	ds_read_b128 v[180:183], v157 offset:2048
	ds_read_b128 v[184:187], v157 offset:3072
	v_lshl_add_u64 v[166:167], s[24:25], 0, v[136:137]
	s_add_i32 m0, s38, 0xc000
	ds_read_b128 v[188:191], v156
	ds_read_b128 v[192:195], v156 offset:1024
	ds_read_b128 v[196:199], v156 offset:2048
	ds_read_b128 v[222:225], v156 offset:3072
	ds_read_b128 v[226:229], v156 offset:4096
	ds_read_b128 v[230:233], v156 offset:5120
	ds_read_b128 v[234:237], v156 offset:6144
	ds_read_b128 v[238:241], v156 offset:7168
	global_load_lds_dwordx4 v[166:167], off
	v_lshl_add_u64 v[166:167], s[24:25], 0, v[138:139]
	s_add_i32 m0, s38, 0xe000
	s_nop 0
	global_load_lds_dwordx4 v[166:167], off
	s_waitcnt vmcnt(8)
	s_waitcnt lgkmcnt(0)
	s_barrier
	s_setprio 1
	s_waitcnt lgkmcnt(0)
	v_mfma_f32_16x16x32_bf16 v[126:129], v[140:143], v[188:191], 0
	v_mfma_f32_16x16x32_bf16 v[118:121], v[148:151], v[188:191], 0
	v_mfma_f32_16x16x32_bf16 v[110:113], v[140:143], v[196:199], 0
	v_mfma_f32_16x16x32_bf16 v[102:105], v[148:151], v[196:199], 0
	v_mfma_f32_16x16x32_bf16 v[94:97], v[140:143], v[226:229], 0
	v_mfma_f32_16x16x32_bf16 v[86:89], v[148:151], v[226:229], 0
	v_mfma_f32_16x16x32_bf16 v[78:81], v[140:143], v[234:237], 0
	v_mfma_f32_16x16x32_bf16 v[70:73], v[148:151], v[234:237], 0
	v_mfma_f32_16x16x32_bf16 v[126:129], v[144:147], v[192:195], v[126:129]
	v_mfma_f32_16x16x32_bf16 v[118:121], v[158:161], v[192:195], v[118:121]
	v_mfma_f32_16x16x32_bf16 v[110:113], v[144:147], v[222:225], v[110:113]
	v_mfma_f32_16x16x32_bf16 v[102:105], v[158:161], v[222:225], v[102:105]
	v_mfma_f32_16x16x32_bf16 v[94:97], v[144:147], v[230:233], v[94:97]
	v_mfma_f32_16x16x32_bf16 v[86:89], v[158:161], v[230:233], v[86:89]
	v_mfma_f32_16x16x32_bf16 v[78:81], v[144:147], v[238:241], v[78:81]
	v_mfma_f32_16x16x32_bf16 v[70:73], v[158:161], v[238:241], v[70:73]
	s_setprio 0
	s_setprio 1
	v_mfma_f32_16x16x32_bf16 v[122:125], v[162:165], v[188:191], 0
	v_mfma_f32_16x16x32_bf16 v[114:117], v[180:183], v[188:191], 0
	v_mfma_f32_16x16x32_bf16 v[106:109], v[162:165], v[196:199], 0
	v_mfma_f32_16x16x32_bf16 v[98:101], v[180:183], v[196:199], 0
	v_mfma_f32_16x16x32_bf16 v[90:93], v[162:165], v[226:229], 0
	v_mfma_f32_16x16x32_bf16 v[82:85], v[180:183], v[226:229], 0
	v_mfma_f32_16x16x32_bf16 v[74:77], v[162:165], v[234:237], 0
	v_mfma_f32_16x16x32_bf16 v[66:69], v[180:183], v[234:237], 0
	v_mfma_f32_16x16x32_bf16 v[122:125], v[176:179], v[192:195], v[122:125]
	v_mfma_f32_16x16x32_bf16 v[114:117], v[184:187], v[192:195], v[114:117]
	v_mfma_f32_16x16x32_bf16 v[106:109], v[176:179], v[222:225], v[106:109]
	v_mfma_f32_16x16x32_bf16 v[98:101], v[184:187], v[222:225], v[98:101]
	v_mfma_f32_16x16x32_bf16 v[90:93], v[176:179], v[230:233], v[90:93]
	v_mfma_f32_16x16x32_bf16 v[82:85], v[184:187], v[230:233], v[82:85]
	v_mfma_f32_16x16x32_bf16 v[74:77], v[176:179], v[238:241], v[74:77]
	v_mfma_f32_16x16x32_bf16 v[66:69], v[184:187], v[238:241], v[66:69]
	s_setprio 0
	s_barrier
	s_add_i32 s49, s49, s37
	v_lshl_add_u64 v[166:167], s[26:27], 0, v[168:169]
	s_mov_b32 m0, s49
	ds_read_b128 v[188:191], v156 offset:16384
	ds_read_b128 v[192:195], v156 offset:17408
	ds_read_b128 v[196:199], v156 offset:18432
	ds_read_b128 v[222:225], v156 offset:19456
	ds_read_b128 v[226:229], v156 offset:20480
	ds_read_b128 v[230:233], v156 offset:21504
	ds_read_b128 v[234:237], v156 offset:22528
	ds_read_b128 v[238:241], v156 offset:23552
	global_load_lds_dwordx4 v[166:167], off
	s_add_i32 m0, s49, 0x2000
	s_add_u32 s94, s26, 0x80000
	v_lshl_add_u64 v[200:201], s[26:27], 0, v[134:135]
	s_addc_u32 s95, s27, 0
	s_add_i32 s49, s82, s37
	global_load_lds_dwordx4 v[200:201], off
	v_lshl_add_u64 v[242:243], s[94:95], 0, v[168:169]
	s_mov_b32 m0, s49
	v_lshl_add_u64 v[244:245], s[28:29], 0, v[132:133]
	global_load_lds_dwordx4 v[242:243], off
	v_lshl_add_u64 v[242:243], s[94:95], 0, v[134:135]
	s_add_i32 m0, s49, 0x2000
	s_nop 0
	global_load_lds_dwordx4 v[242:243], off
	v_lshl_add_u64 v[242:243], s[28:29], 0, v[130:131]
	s_mov_b32 m0, s38
	s_nop 0
	global_load_lds_dwordx4 v[242:243], off
	s_mov_b32 m0, s39
	s_nop 0
	global_load_lds_dwordx4 v[244:245], off
	s_waitcnt vmcnt(8)
	s_waitcnt lgkmcnt(0)
	s_barrier
; #define PG8_STAGE(bufoff, gbase, voff) do { _Pragma("unroll") for (int _i = 0; _i < 2; ++_i) \
;         __builtin_amdgcn_global_load_lds((const unsigned*)((const char*)(gbase) + (voff)[_i]), (LAS unsigned*)(lds + (bufoff) + ldsw + _i * 8192), 16, 0, 0); } while (0)
; #define PG8_LDA(dst, b, h) do { _Pragma("unroll") for (int m = 0; m < 4; ++m) _Pragma("unroll") for (int k = 0; k < 2; ++k) dst[m][k] = *(const LAS bf16x8*)(lds + PG8_SA(b, h) + aoff + m * 2048 + k * 1024); } while (0)
; #define PG8_LDB(dst, b, h) do { _Pragma("unroll") for (int n = 0; n < 2; ++n) _Pragma("unroll") for (int k = 0; k < 2; ++k) dst[n][k] = *(const LAS bf16x8*)(lds + PG8_SB(b, h) + boff + n * 2048 + k * 1024); } while (0)
; #define PG8_MMA(ai, bj, At, Bt) do { __builtin_amdgcn_s_setprio(1); _Pragma("unroll") for (int m = 0; m < 4; ++m) _Pragma("unroll") for (int n = 0; n < 2; ++n) _Pragma("unroll") for (int k = 0; k < 2; ++k) \
;         acc[ai][bj][m][n] = __builtin_amdgcn_mfma_f32_16x16x32_bf16(Bt[n][k], At[m][k], acc[ai][bj][m][n], 0, 0, 0); __builtin_amdgcn_s_setprio(0); } while (0)
; #define PG8_WAIT_V(n) asm volatile("s_waitcnt vmcnt(" #n ")" ::: "memory")
; #define PG8_WAIT_L(n) asm volatile("s_waitcnt lgkmcnt(" #n ")" ::: "memory")
; #define PG8_BAR __builtin_amdgcn_s_barrier()
; #define PG8_SCHED __builtin_amdgcn_sched_barrier(0)
; template <class Epi>
; __device__ __forceinline__ void gemm_phase(LAS unsigned char* lds, const Sched& S, const Epi& E) {
;     ...
;             PG8_LDA(At, 0, 1); PG8_STAGE(PG8_SB(0, 0), b2, voffB); PG8_STAGE(PG8_SB(0, 1), b2 + hstepB, voffB); PG8_STAGE(PG8_SA(0, 0), a2, voffA);
;             PG8_WAIT_V(8); PG8_WAIT_L(0); PG8_BAR; PG8_MMA(1, 0, At, B0); PG8_MMA(1, 1, At, B1); PG8_BAR; PG8_SCHED;
;             PG8_LDB(B0, 1, 0); PG8_LDB(B1, 1, 1); PG8_SCHED; PG8_LDA(At, 1, 0); PG8_STAGE(PG8_SA(0, 1), a2 + hstepA, voffA);
;             PG8_WAIT_V(8); PG8_WAIT_L(0); PG8_BAR; PG8_MMA(0, 0, At, B0); PG8_MMA(0, 1, At, B1); PG8_BAR; PG8_SCHED;
	s_setprio 1
	s_waitcnt lgkmcnt(0)
	v_mfma_f32_16x16x32_bf16 v[62:65], v[140:143], v[188:191], 0
	v_mfma_f32_16x16x32_bf16 v[54:57], v[148:151], v[188:191], 0
	v_mfma_f32_16x16x32_bf16 v[46:49], v[140:143], v[196:199], 0
	v_mfma_f32_16x16x32_bf16 v[38:41], v[148:151], v[196:199], 0
	v_mfma_f32_16x16x32_bf16 v[30:33], v[140:143], v[226:229], 0
	v_mfma_f32_16x16x32_bf16 v[22:25], v[148:151], v[226:229], 0
	v_mfma_f32_16x16x32_bf16 v[14:17], v[140:143], v[234:237], 0
	v_mfma_f32_16x16x32_bf16 v[6:9], v[148:151], v[234:237], 0
	v_mfma_f32_16x16x32_bf16 v[62:65], v[144:147], v[192:195], v[62:65]
	v_mfma_f32_16x16x32_bf16 v[54:57], v[158:161], v[192:195], v[54:57]
	v_mfma_f32_16x16x32_bf16 v[46:49], v[144:147], v[222:225], v[46:49]
	v_mfma_f32_16x16x32_bf16 v[38:41], v[158:161], v[222:225], v[38:41]
	v_mfma_f32_16x16x32_bf16 v[30:33], v[144:147], v[230:233], v[30:33]
	v_mfma_f32_16x16x32_bf16 v[22:25], v[158:161], v[230:233], v[22:25]
	v_mfma_f32_16x16x32_bf16 v[14:17], v[144:147], v[238:241], v[14:17]
	v_mfma_f32_16x16x32_bf16 v[6:9], v[158:161], v[238:241], v[6:9]
	s_setprio 0
	s_setprio 1
	v_mfma_f32_16x16x32_bf16 v[58:61], v[162:165], v[188:191], 0
	v_mfma_f32_16x16x32_bf16 v[50:53], v[180:183], v[188:191], 0
	v_mfma_f32_16x16x32_bf16 v[42:45], v[162:165], v[196:199], 0
	v_mfma_f32_16x16x32_bf16 v[34:37], v[180:183], v[196:199], 0
	v_mfma_f32_16x16x32_bf16 v[26:29], v[162:165], v[226:229], 0
	v_mfma_f32_16x16x32_bf16 v[18:21], v[180:183], v[226:229], 0
	v_mfma_f32_16x16x32_bf16 v[10:13], v[162:165], v[234:237], 0
	v_mfma_f32_16x16x32_bf16 v[2:5], v[180:183], v[234:237], 0
	v_mfma_f32_16x16x32_bf16 v[58:61], v[176:179], v[192:195], v[58:61]
	v_mfma_f32_16x16x32_bf16 v[50:53], v[184:187], v[192:195], v[50:53]
	v_mfma_f32_16x16x32_bf16 v[42:45], v[176:179], v[222:225], v[42:45]
	v_mfma_f32_16x16x32_bf16 v[34:37], v[184:187], v[222:225], v[34:37]
	v_mfma_f32_16x16x32_bf16 v[26:29], v[176:179], v[230:233], v[26:29]
	v_mfma_f32_16x16x32_bf16 v[18:21], v[184:187], v[230:233], v[18:21]
	v_mfma_f32_16x16x32_bf16 v[10:13], v[176:179], v[238:241], v[10:13]
	v_mfma_f32_16x16x32_bf16 v[2:5], v[184:187], v[238:241], v[2:5]
	s_setprio 0
	s_barrier
	s_add_i32 s49, 0, 0x18000
	v_add_u32_e32 v157, s49, v153
	s_add_i32 s82, 0, 0x1c000
	ds_read_b128 v[140:143], v157
	ds_read_b128 v[144:147], v157 offset:1024
	ds_read_b128 v[148:151], v157 offset:2048
	ds_read_b128 v[158:161], v157 offset:3072
	v_add_u32_e32 v157, s82, v153
	ds_read_b128 v[162:165], v157
	ds_read_b128 v[176:179], v157 offset:1024
	ds_read_b128 v[180:183], v157 offset:2048
	ds_read_b128 v[184:187], v157 offset:3072
	s_add_u32 s28, s28, 0x80000
	s_addc_u32 s29, s29, 0
	s_mov_b32 m0, s58
	v_lshl_add_u64 v[246:247], s[28:29], 0, v[130:131]
	ds_read_b128 v[188:191], v156 offset:32768
	ds_read_b128 v[192:195], v156 offset:33792
	ds_read_b128 v[196:199], v156 offset:34816
	ds_read_b128 v[222:225], v156 offset:35840
	ds_read_b128 v[226:229], v156 offset:36864
	ds_read_b128 v[230:233], v156 offset:37888
	ds_read_b128 v[234:237], v156 offset:38912
	ds_read_b128 v[238:241], v156 offset:39936
	global_load_lds_dwordx4 v[246:247], off
	v_lshl_add_u64 v[246:247], s[28:29], 0, v[132:133]
	s_mov_b32 m0, s59
	s_nop 0
	global_load_lds_dwordx4 v[246:247], off
	s_waitcnt vmcnt(8)
	s_waitcnt lgkmcnt(0)
	s_barrier
	s_setprio 1
	s_waitcnt lgkmcnt(0)
	v_mfma_f32_16x16x32_bf16 v[126:129], v[140:143], v[188:191], v[126:129]
	v_mfma_f32_16x16x32_bf16 v[118:121], v[148:151], v[188:191], v[118:121]
	v_mfma_f32_16x16x32_bf16 v[110:113], v[140:143], v[196:199], v[110:113]
	v_mfma_f32_16x16x32_bf16 v[102:105], v[148:151], v[196:199], v[102:105]
	v_mfma_f32_16x16x32_bf16 v[94:97], v[140:143], v[226:229], v[94:97]
	v_mfma_f32_16x16x32_bf16 v[86:89], v[148:151], v[226:229], v[86:89]
	v_mfma_f32_16x16x32_bf16 v[78:81], v[140:143], v[234:237], v[78:81]
	v_mfma_f32_16x16x32_bf16 v[70:73], v[148:151], v[234:237], v[70:73]
	v_mfma_f32_16x16x32_bf16 v[126:129], v[144:147], v[192:195], v[126:129]
	v_mfma_f32_16x16x32_bf16 v[118:121], v[158:161], v[192:195], v[118:121]
	v_mfma_f32_16x16x32_bf16 v[110:113], v[144:147], v[222:225], v[110:113]
	v_mfma_f32_16x16x32_bf16 v[102:105], v[158:161], v[222:225], v[102:105]
	v_mfma_f32_16x16x32_bf16 v[94:97], v[144:147], v[230:233], v[94:97]
	v_mfma_f32_16x16x32_bf16 v[86:89], v[158:161], v[230:233], v[86:89]
	v_mfma_f32_16x16x32_bf16 v[78:81], v[144:147], v[238:241], v[78:81]
	v_mfma_f32_16x16x32_bf16 v[70:73], v[158:161], v[238:241], v[70:73]
	s_setprio 0
	s_setprio 1
	v_mfma_f32_16x16x32_bf16 v[122:125], v[162:165], v[188:191], v[122:125]
	v_mfma_f32_16x16x32_bf16 v[114:117], v[180:183], v[188:191], v[114:117]
	v_mfma_f32_16x16x32_bf16 v[106:109], v[162:165], v[196:199], v[106:109]
	v_mfma_f32_16x16x32_bf16 v[98:101], v[180:183], v[196:199], v[98:101]
	v_mfma_f32_16x16x32_bf16 v[90:93], v[162:165], v[226:229], v[90:93]
	v_mfma_f32_16x16x32_bf16 v[82:85], v[180:183], v[226:229], v[82:85]
	v_mfma_f32_16x16x32_bf16 v[74:77], v[162:165], v[234:237], v[74:77]
	v_mfma_f32_16x16x32_bf16 v[66:69], v[180:183], v[234:237], v[66:69]
	v_mfma_f32_16x16x32_bf16 v[122:125], v[176:179], v[192:195], v[122:125]
	v_mfma_f32_16x16x32_bf16 v[114:117], v[184:187], v[192:195], v[114:117]
	v_mfma_f32_16x16x32_bf16 v[106:109], v[176:179], v[222:225], v[106:109]
	v_mfma_f32_16x16x32_bf16 v[98:101], v[184:187], v[222:225], v[98:101]
	v_mfma_f32_16x16x32_bf16 v[90:93], v[176:179], v[230:233], v[90:93]
	v_mfma_f32_16x16x32_bf16 v[82:85], v[184:187], v[230:233], v[82:85]
	v_mfma_f32_16x16x32_bf16 v[74:77], v[176:179], v[238:241], v[74:77]
	v_mfma_f32_16x16x32_bf16 v[66:69], v[184:187], v[238:241], v[66:69]
	s_setprio 0
	s_barrier
; #define PG8_STAGE(bufoff, gbase, voff) do { _Pragma("unroll") for (int _i = 0; _i < 2; ++_i) \
;         __builtin_amdgcn_global_load_lds((const unsigned*)((const char*)(gbase) + (voff)[_i]), (LAS unsigned*)(lds + (bufoff) + ldsw + _i * 8192), 16, 0, 0); } while (0)
; #define PG8_LDA(dst, b, h) do { _Pragma("unroll") for (int m = 0; m < 4; ++m) _Pragma("unroll") for (int k = 0; k < 2; ++k) dst[m][k] = *(const LAS bf16x8*)(lds + PG8_SA(b, h) + aoff + m * 2048 + k * 1024); } while (0)
; #define PG8_MMA(ai, bj, At, Bt) do { __builtin_amdgcn_s_setprio(1); _Pragma("unroll") for (int m = 0; m < 4; ++m) _Pragma("unroll") for (int n = 0; n < 2; ++n) _Pragma("unroll") for (int k = 0; k < 2; ++k) \
;         acc[ai][bj][m][n] = __builtin_amdgcn_mfma_f32_16x16x32_bf16(Bt[n][k], At[m][k], acc[ai][bj][m][n], 0, 0, 0); __builtin_amdgcn_s_setprio(0); } while (0)
; #define PG8_WAIT_V(n) asm volatile("s_waitcnt vmcnt(" #n ")" ::: "memory")
; #define PG8_WAIT_L(n) asm volatile("s_waitcnt lgkmcnt(" #n ")" ::: "memory")
; #define PG8_BAR __builtin_amdgcn_s_barrier()
; #define PG8_SCHED __builtin_amdgcn_sched_barrier(0)
; template <class Epi>
; __device__ __forceinline__ void gemm_phase(LAS unsigned char* lds, const Sched& S, const Epi& E) {
;     ...
;             PG8_LDA(At, 1, 1); PG8_STAGE(PG8_SB(1, 0), b3, voffB); PG8_STAGE(PG8_SB(1, 1), b3 + hstepB, voffB); PG8_STAGE(PG8_SA(1, 0), a3, voffA);
;             PG8_WAIT_V(8); PG8_WAIT_L(0); PG8_BAR; PG8_MMA(1, 0, At, B0); PG8_MMA(1, 1, At, B1); PG8_BAR; PG8_SCHED;
;         }
	s_add_i32 s28, s49, s37
	v_lshl_add_u64 v[166:167], v[166:167], 0, s[0:1]
	s_mov_b32 m0, s28
	ds_read_b128 v[188:191], v156 offset:49152
	ds_read_b128 v[192:195], v156 offset:50176
	ds_read_b128 v[196:199], v156 offset:51200
	ds_read_b128 v[222:225], v156 offset:52224
	ds_read_b128 v[226:229], v156 offset:53248
	ds_read_b128 v[230:233], v156 offset:54272
	ds_read_b128 v[234:237], v156 offset:55296
	ds_read_b128 v[238:241], v156 offset:56320
	global_load_lds_dwordx4 v[166:167], off
	s_add_i32 m0, s28, 0x2000
	s_add_u32 s26, s26, 0x80080
	v_lshl_add_u64 v[166:167], v[200:201], 0, s[0:1]
	s_addc_u32 s27, s27, 0
	s_add_i32 s28, s82, s37
	global_load_lds_dwordx4 v[166:167], off
	v_lshl_add_u64 v[166:167], s[26:27], 0, v[168:169]
	s_mov_b32 m0, s28
	s_nop 0
	global_load_lds_dwordx4 v[166:167], off
	v_lshl_add_u64 v[166:167], s[26:27], 0, v[134:135]
	s_add_i32 m0, s28, 0x2000
	s_nop 0
	global_load_lds_dwordx4 v[166:167], off
	v_lshl_add_u64 v[166:167], v[242:243], 0, s[0:1]
	s_mov_b32 m0, s64
	s_nop 0
	global_load_lds_dwordx4 v[166:167], off
	v_lshl_add_u64 v[166:167], v[244:245], 0, s[0:1]
	s_mov_b32 m0, s65
	s_nop 0
	global_load_lds_dwordx4 v[166:167], off
	s_waitcnt vmcnt(8)
	s_waitcnt lgkmcnt(0)
	s_barrier
	s_setprio 1
	s_waitcnt lgkmcnt(0)
	v_mfma_f32_16x16x32_bf16 v[62:65], v[140:143], v[188:191], v[62:65]
	v_mfma_f32_16x16x32_bf16 v[54:57], v[148:151], v[188:191], v[54:57]
	v_mfma_f32_16x16x32_bf16 v[46:49], v[140:143], v[196:199], v[46:49]
	v_mfma_f32_16x16x32_bf16 v[38:41], v[148:151], v[196:199], v[38:41]
	v_mfma_f32_16x16x32_bf16 v[30:33], v[140:143], v[226:229], v[30:33]
	v_mfma_f32_16x16x32_bf16 v[22:25], v[148:151], v[226:229], v[22:25]
	v_mfma_f32_16x16x32_bf16 v[14:17], v[140:143], v[234:237], v[14:17]
	v_mfma_f32_16x16x32_bf16 v[6:9], v[148:151], v[234:237], v[6:9]
	v_mfma_f32_16x16x32_bf16 v[62:65], v[144:147], v[192:195], v[62:65]
	v_mfma_f32_16x16x32_bf16 v[54:57], v[158:161], v[192:195], v[54:57]
	v_mfma_f32_16x16x32_bf16 v[46:49], v[144:147], v[222:225], v[46:49]
	v_mfma_f32_16x16x32_bf16 v[38:41], v[158:161], v[222:225], v[38:41]
	v_mfma_f32_16x16x32_bf16 v[30:33], v[144:147], v[230:233], v[30:33]
	v_mfma_f32_16x16x32_bf16 v[22:25], v[158:161], v[230:233], v[22:25]
	v_mfma_f32_16x16x32_bf16 v[14:17], v[144:147], v[238:241], v[14:17]
	v_mfma_f32_16x16x32_bf16 v[6:9], v[158:161], v[238:241], v[6:9]
	s_setprio 0
	s_setprio 1
	v_mfma_f32_16x16x32_bf16 v[58:61], v[162:165], v[188:191], v[58:61]
	v_mfma_f32_16x16x32_bf16 v[50:53], v[180:183], v[188:191], v[50:53]
	v_mfma_f32_16x16x32_bf16 v[42:45], v[162:165], v[196:199], v[42:45]
	v_mfma_f32_16x16x32_bf16 v[34:37], v[180:183], v[196:199], v[34:37]
	v_mfma_f32_16x16x32_bf16 v[26:29], v[162:165], v[226:229], v[26:29]
	v_mfma_f32_16x16x32_bf16 v[18:21], v[180:183], v[226:229], v[18:21]
	v_mfma_f32_16x16x32_bf16 v[10:13], v[162:165], v[234:237], v[10:13]
	v_mfma_f32_16x16x32_bf16 v[2:5], v[180:183], v[234:237], v[2:5]
	v_mfma_f32_16x16x32_bf16 v[58:61], v[176:179], v[192:195], v[58:61]
	v_mfma_f32_16x16x32_bf16 v[50:53], v[184:187], v[192:195], v[50:53]
	v_mfma_f32_16x16x32_bf16 v[42:45], v[176:179], v[222:225], v[42:45]
	v_mfma_f32_16x16x32_bf16 v[34:37], v[184:187], v[222:225], v[34:37]
	v_mfma_f32_16x16x32_bf16 v[26:29], v[176:179], v[230:233], v[26:29]
	v_mfma_f32_16x16x32_bf16 v[18:21], v[184:187], v[230:233], v[18:21]
	v_mfma_f32_16x16x32_bf16 v[10:13], v[176:179], v[238:241], v[10:13]
	v_mfma_f32_16x16x32_bf16 v[2:5], v[184:187], v[238:241], v[2:5]
	s_setprio 0
	s_barrier
	s_add_i32 s69, s69, 2
	s_add_u32 s24, s24, 0x100
	s_addc_u32 s25, s25, 0
	s_add_u32 s9, s9, 0x100
	s_addc_u32 s11, s11, 0
	s_cmp_gt_u32 s69, 29
	s_cbranch_scc1 .Lpeel_exit_gateup

; #define PG8_STAGE(bufoff, gbase, voff) do { _Pragma("unroll") for (int _i = 0; _i < 2; ++_i) \
;         __builtin_amdgcn_global_load_lds((const unsigned*)((const char*)(gbase) + (voff)[_i]), (LAS unsigned*)(lds + (bufoff) + ldsw + _i * 8192), 16, 0, 0); } while (0)
; #define PG8_LDA(dst, b, h) do { _Pragma("unroll") for (int m = 0; m < 4; ++m) _Pragma("unroll") for (int k = 0; k < 2; ++k) dst[m][k] = *(const LAS bf16x8*)(lds + PG8_SA(b, h) + aoff + m * 2048 + k * 1024); } while (0)
; #define PG8_LDB(dst, b, h) do { _Pragma("unroll") for (int n = 0; n < 2; ++n) _Pragma("unroll") for (int k = 0; k < 2; ++k) dst[n][k] = *(const LAS bf16x8*)(lds + PG8_SB(b, h) + boff + n * 2048 + k * 1024); } while (0)
; #define PG8_MMA(ai, bj, At, Bt) do { __builtin_amdgcn_s_setprio(1); _Pragma("unroll") for (int m = 0; m < 4; ++m) _Pragma("unroll") for (int n = 0; n < 2; ++n) _Pragma("unroll") for (int k = 0; k < 2; ++k) \
;         acc[ai][bj][m][n] = __builtin_amdgcn_mfma_f32_16x16x32_bf16(Bt[n][k], At[m][k], acc[ai][bj][m][n], 0, 0, 0); __builtin_amdgcn_s_setprio(0); } while (0)
; #define PG8_WAIT_V(n) asm volatile("s_waitcnt vmcnt(" #n ")" ::: "memory")
; #define PG8_WAIT_L(n) asm volatile("s_waitcnt lgkmcnt(" #n ")" ::: "memory")
; #define PG8_BAR __builtin_amdgcn_s_barrier()
; #define PG8_SCHED __builtin_amdgcn_sched_barrier(0)
; template <class Epi>
; __device__ __forceinline__ void gemm_phase(LAS unsigned char* lds, const Sched& S, const Epi& E) {
;     ...
;             const bool last = (t == nt - 2);
;             const char* a1 = cA + (size_t)(t + 1) * kstep;
;             const char* a2 = last ? nA : cA + (size_t)(t + 2) * kstep; const char* b2 = last ? nB : cB + (size_t)(t + 2) * kstep;
;             const char* a3 = a2 + kstep; const char* b3 = b2 + kstep;
;             PG8_LDB(B0, 0, 0); PG8_LDB(B1, 0, 1); PG8_SCHED; PG8_LDA(At, 0, 0); PG8_STAGE(PG8_SA(1, 1), a1 + hstepA, voffA);
;             PG8_WAIT_V(8); PG8_WAIT_L(0); PG8_BAR; PG8_MMA(0, 0, At, B0); PG8_MMA(0, 1, At, B1); PG8_BAR; PG8_SCHED;
.LBB0_2390:
	s_and_b64 s[24:25], s[18:19], exec
	s_cselect_b32 s26, s15, s5
	s_cselect_b32 s27, s14, s4
	s_cselect_b32 s95, s17, s23
	s_cselect_b32 s96, s16, s22
	s_add_i32 s97, s94, -2
	s_add_u32 s4, s4, 0x160080
	s_addc_u32 s5, s5, 0
	s_add_u32 vcc_lo, s22, 0x100
	v_mov_b32_e32 v2, 0
	s_mov_b64 s[52:53], s[72:73]
	s_addc_u32 vcc_hi, s23, 0
	s_mov_b32 s22, 0
	s_waitcnt lgkmcnt(0)
	s_add_i32 s49, s22, 2
	s_add_u32 s23, s4, 0xffea0080
	s_addc_u32 s24, s5, -1
	s_add_i32 s88, 0, 0x10000
	s_cmp_eq_u32 s97, s22
	s_cselect_b32 s25, s26, s24
	s_cselect_b32 s24, s27, s23
	s_cselect_b32 s23, s95, vcc_hi
	s_cselect_b32 s22, s96, vcc_lo
	s_add_i32 s72, 0, 0x14000
	v_add_u32_e32 v142, s88, v222
	v_add_u32_e32 v158, s72, v222
	ds_read_b128 v[130:133], v142
	ds_read_b128 v[134:137], v142 offset:1024
	ds_read_b128 v[138:141], v142 offset:2048
	ds_read_b128 v[142:145], v142 offset:3072
	ds_read_b128 v[146:149], v158
	ds_read_b128 v[150:153], v158 offset:1024
	ds_read_b128 v[154:157], v158 offset:2048
	ds_read_b128 v[158:161], v158 offset:3072
	v_lshl_add_u64 v[166:167], s[4:5], 0, v[186:187]
	s_add_i32 m0, s35, 0xc000
	ds_read_b128 v[162:165], v224
	ds_read_b128 v[190:193], v224 offset:1024
	ds_read_b128 v[194:197], v224 offset:2048
	ds_read_b128 v[198:201], v224 offset:3072
	ds_read_b128 v[226:229], v224 offset:4096
	ds_read_b128 v[230:233], v224 offset:5120
	ds_read_b128 v[234:237], v224 offset:6144
	ds_read_b128 v[238:241], v224 offset:7168
	global_load_lds_dwordx4 v[166:167], off
	v_lshl_add_u64 v[166:167], s[4:5], 0, v[188:189]
	s_add_i32 m0, s35, 0xe000
	s_nop 0
	global_load_lds_dwordx4 v[166:167], off
	s_waitcnt vmcnt(8)
	s_waitcnt lgkmcnt(0)
	s_barrier
	s_setprio 1
	s_waitcnt lgkmcnt(0)
	v_mfma_f32_16x16x32_bf16 v[126:129], v[130:133], v[162:165], 0
	v_mfma_f32_16x16x32_bf16 v[122:125], v[138:141], v[162:165], 0
	v_mfma_f32_16x16x32_bf16 v[118:121], v[130:133], v[194:197], 0
	v_mfma_f32_16x16x32_bf16 v[106:109], v[138:141], v[194:197], 0
	v_mfma_f32_16x16x32_bf16 v[94:97], v[130:133], v[226:229], 0
	v_mfma_f32_16x16x32_bf16 v[90:93], v[138:141], v[226:229], 0
	v_mfma_f32_16x16x32_bf16 v[86:89], v[130:133], v[234:237], 0
	v_mfma_f32_16x16x32_bf16 v[74:77], v[138:141], v[234:237], 0
	v_mfma_f32_16x16x32_bf16 v[126:129], v[134:137], v[190:193], v[126:129]
	v_mfma_f32_16x16x32_bf16 v[122:125], v[142:145], v[190:193], v[122:125]
	v_mfma_f32_16x16x32_bf16 v[118:121], v[134:137], v[198:201], v[118:121]
	v_mfma_f32_16x16x32_bf16 v[106:109], v[142:145], v[198:201], v[106:109]
	v_mfma_f32_16x16x32_bf16 v[94:97], v[134:137], v[230:233], v[94:97]
	v_mfma_f32_16x16x32_bf16 v[90:93], v[142:145], v[230:233], v[90:93]
	v_mfma_f32_16x16x32_bf16 v[86:89], v[134:137], v[238:241], v[86:89]
	v_mfma_f32_16x16x32_bf16 v[74:77], v[142:145], v[238:241], v[74:77]
	s_setprio 0
	s_setprio 1
	v_mfma_f32_16x16x32_bf16 v[114:117], v[146:149], v[162:165], 0
	v_mfma_f32_16x16x32_bf16 v[110:113], v[154:157], v[162:165], 0
	v_mfma_f32_16x16x32_bf16 v[102:105], v[146:149], v[194:197], 0
	v_mfma_f32_16x16x32_bf16 v[98:101], v[154:157], v[194:197], 0
	v_mfma_f32_16x16x32_bf16 v[82:85], v[146:149], v[226:229], 0
	v_mfma_f32_16x16x32_bf16 v[78:81], v[154:157], v[226:229], 0
	v_mfma_f32_16x16x32_bf16 v[70:73], v[146:149], v[234:237], 0
	v_mfma_f32_16x16x32_bf16 v[66:69], v[154:157], v[234:237], 0
	v_mfma_f32_16x16x32_bf16 v[114:117], v[150:153], v[190:193], v[114:117]
	v_mfma_f32_16x16x32_bf16 v[110:113], v[158:161], v[190:193], v[110:113]
	v_mfma_f32_16x16x32_bf16 v[102:105], v[150:153], v[198:201], v[102:105]
	v_mfma_f32_16x16x32_bf16 v[98:101], v[158:161], v[198:201], v[98:101]
	v_mfma_f32_16x16x32_bf16 v[82:85], v[150:153], v[230:233], v[82:85]
	v_mfma_f32_16x16x32_bf16 v[78:81], v[158:161], v[230:233], v[78:81]
	v_mfma_f32_16x16x32_bf16 v[70:73], v[150:153], v[238:241], v[70:73]
	v_mfma_f32_16x16x32_bf16 v[66:69], v[158:161], v[238:241], v[66:69]
	s_setprio 0
	s_barrier
	s_add_i32 s73, s88, s34
	v_lshl_add_u64 v[166:167], s[22:23], 0, v[168:169]
	s_mov_b32 m0, s73
	ds_read_b128 v[162:165], v224 offset:16384
	ds_read_b128 v[190:193], v224 offset:17408
	ds_read_b128 v[194:197], v224 offset:18432
	ds_read_b128 v[198:201], v224 offset:19456
	ds_read_b128 v[226:229], v224 offset:20480
	ds_read_b128 v[230:233], v224 offset:21504
	ds_read_b128 v[234:237], v224 offset:22528
	ds_read_b128 v[238:241], v224 offset:23552
	global_load_lds_dwordx4 v[166:167], off
	s_add_i32 m0, s73, 0x2000
	s_add_u32 s88, s22, 0x160000
	v_lshl_add_u64 v[242:243], s[22:23], 0, v[176:177]
	s_addc_u32 s89, s23, 0
	s_add_i32 s72, s72, s34
	global_load_lds_dwordx4 v[242:243], off
	v_lshl_add_u64 v[244:245], s[88:89], 0, v[168:169]
	s_mov_b32 m0, s72
	v_lshl_add_u64 v[246:247], s[24:25], 0, v[176:177]
	global_load_lds_dwordx4 v[244:245], off
	v_lshl_add_u64 v[244:245], s[88:89], 0, v[176:177]
	s_add_i32 m0, s72, 0x2000
	s_nop 0
	global_load_lds_dwordx4 v[244:245], off
	v_lshl_add_u64 v[244:245], s[24:25], 0, v[168:169]
	s_mov_b32 m0, s35
	s_nop 0
	global_load_lds_dwordx4 v[244:245], off
	s_mov_b32 m0, s36
	s_nop 0
	global_load_lds_dwordx4 v[246:247], off
	s_waitcnt vmcnt(8)
	s_waitcnt lgkmcnt(0)
	s_barrier
; #define PG8_STAGE(bufoff, gbase, voff) do { _Pragma("unroll") for (int _i = 0; _i < 2; ++_i) \
;         __builtin_amdgcn_global_load_lds((const unsigned*)((const char*)(gbase) + (voff)[_i]), (LAS unsigned*)(lds + (bufoff) + ldsw + _i * 8192), 16, 0, 0); } while (0)
; #define PG8_LDA(dst, b, h) do { _Pragma("unroll") for (int m = 0; m < 4; ++m) _Pragma("unroll") for (int k = 0; k < 2; ++k) dst[m][k] = *(const LAS bf16x8*)(lds + PG8_SA(b, h) + aoff + m * 2048 + k * 1024); } while (0)
; #define PG8_LDB(dst, b, h) do { _Pragma("unroll") for (int n = 0; n < 2; ++n) _Pragma("unroll") for (int k = 0; k < 2; ++k) dst[n][k] = *(const LAS bf16x8*)(lds + PG8_SB(b, h) + boff + n * 2048 + k * 1024); } while (0)
; #define PG8_MMA(ai, bj, At, Bt) do { __builtin_amdgcn_s_setprio(1); _Pragma("unroll") for (int m = 0; m < 4; ++m) _Pragma("unroll") for (int n = 0; n < 2; ++n) _Pragma("unroll") for (int k = 0; k < 2; ++k) \
;         acc[ai][bj][m][n] = __builtin_amdgcn_mfma_f32_16x16x32_bf16(Bt[n][k], At[m][k], acc[ai][bj][m][n], 0, 0, 0); __builtin_amdgcn_s_setprio(0); } while (0)
; #define PG8_WAIT_V(n) asm volatile("s_waitcnt vmcnt(" #n ")" ::: "memory")
; #define PG8_WAIT_L(n) asm volatile("s_waitcnt lgkmcnt(" #n ")" ::: "memory")
; #define PG8_BAR __builtin_amdgcn_s_barrier()
; #define PG8_SCHED __builtin_amdgcn_sched_barrier(0)
; template <class Epi>
; __device__ __forceinline__ void gemm_phase(LAS unsigned char* lds, const Sched& S, const Epi& E) {
;     ...
;             PG8_WAIT_V(8); PG8_WAIT_L(0); PG8_BAR; PG8_MMA(1, 0, At, B0); PG8_MMA(1, 1, At, B1); PG8_BAR; PG8_SCHED;
;             PG8_LDB(B0, 1, 0); PG8_LDB(B1, 1, 1); PG8_SCHED; PG8_LDA(At, 1, 0); PG8_STAGE(PG8_SA(0, 1), a2 + hstepA, voffA);
;             PG8_WAIT_V(8); PG8_WAIT_L(0); PG8_BAR; PG8_MMA(0, 0, At, B0); PG8_MMA(0, 1, At, B1); PG8_BAR; PG8_SCHED;
	s_setprio 1
	s_waitcnt lgkmcnt(0)
	v_mfma_f32_16x16x32_bf16 v[62:65], v[130:133], v[162:165], 0
	v_mfma_f32_16x16x32_bf16 v[58:61], v[138:141], v[162:165], 0
	v_mfma_f32_16x16x32_bf16 v[54:57], v[130:133], v[194:197], 0
	v_mfma_f32_16x16x32_bf16 v[42:45], v[138:141], v[194:197], 0
	v_mfma_f32_16x16x32_bf16 v[30:33], v[130:133], v[226:229], 0
	v_mfma_f32_16x16x32_bf16 v[26:29], v[138:141], v[226:229], 0
	v_mfma_f32_16x16x32_bf16 v[22:25], v[130:133], v[234:237], 0
	v_mfma_f32_16x16x32_bf16 v[10:13], v[138:141], v[234:237], 0
	v_mfma_f32_16x16x32_bf16 v[62:65], v[134:137], v[190:193], v[62:65]
	v_mfma_f32_16x16x32_bf16 v[58:61], v[142:145], v[190:193], v[58:61]
	v_mfma_f32_16x16x32_bf16 v[54:57], v[134:137], v[198:201], v[54:57]
	v_mfma_f32_16x16x32_bf16 v[42:45], v[142:145], v[198:201], v[42:45]
	v_mfma_f32_16x16x32_bf16 v[30:33], v[134:137], v[230:233], v[30:33]
	v_mfma_f32_16x16x32_bf16 v[26:29], v[142:145], v[230:233], v[26:29]
	v_mfma_f32_16x16x32_bf16 v[22:25], v[134:137], v[238:241], v[22:25]
	v_mfma_f32_16x16x32_bf16 v[10:13], v[142:145], v[238:241], v[10:13]
	s_setprio 0
	s_setprio 1
	v_mfma_f32_16x16x32_bf16 v[50:53], v[146:149], v[162:165], 0
	v_mfma_f32_16x16x32_bf16 v[46:49], v[154:157], v[162:165], 0
	v_mfma_f32_16x16x32_bf16 v[38:41], v[146:149], v[194:197], 0
	v_mfma_f32_16x16x32_bf16 v[34:37], v[154:157], v[194:197], 0
	v_mfma_f32_16x16x32_bf16 v[18:21], v[146:149], v[226:229], 0
	v_mfma_f32_16x16x32_bf16 v[14:17], v[154:157], v[226:229], 0
	v_mfma_f32_16x16x32_bf16 v[6:9], v[146:149], v[234:237], 0
	v_mfma_f32_16x16x32_bf16 v[2:5], v[154:157], v[234:237], 0
	v_mfma_f32_16x16x32_bf16 v[50:53], v[150:153], v[190:193], v[50:53]
	v_mfma_f32_16x16x32_bf16 v[46:49], v[158:161], v[190:193], v[46:49]
	v_mfma_f32_16x16x32_bf16 v[38:41], v[150:153], v[198:201], v[38:41]
	v_mfma_f32_16x16x32_bf16 v[34:37], v[158:161], v[198:201], v[34:37]
	v_mfma_f32_16x16x32_bf16 v[18:21], v[150:153], v[230:233], v[18:21]
	v_mfma_f32_16x16x32_bf16 v[14:17], v[158:161], v[230:233], v[14:17]
	v_mfma_f32_16x16x32_bf16 v[6:9], v[150:153], v[238:241], v[6:9]
	v_mfma_f32_16x16x32_bf16 v[2:5], v[158:161], v[238:241], v[2:5]
	s_setprio 0
	s_barrier
	s_add_i32 s72, 0, 0x18000
	s_add_i32 s73, 0, 0x1c000
	v_add_u32_e32 v142, s72, v222
	v_add_u32_e32 v158, s73, v222
	ds_read_b128 v[130:133], v142
	ds_read_b128 v[134:137], v142 offset:1024
	ds_read_b128 v[138:141], v142 offset:2048
	ds_read_b128 v[142:145], v142 offset:3072
	ds_read_b128 v[146:149], v158
	ds_read_b128 v[150:153], v158 offset:1024
	ds_read_b128 v[154:157], v158 offset:2048
	ds_read_b128 v[158:161], v158 offset:3072
	s_add_u32 s24, s24, 0x160000
	s_addc_u32 s25, s25, 0
	s_mov_b32 m0, s37
	v_lshl_add_u64 v[248:249], s[24:25], 0, v[168:169]
	ds_read_b128 v[162:165], v224 offset:32768
	ds_read_b128 v[190:193], v224 offset:33792
	ds_read_b128 v[194:197], v224 offset:34816
	ds_read_b128 v[198:201], v224 offset:35840
	ds_read_b128 v[226:229], v224 offset:36864
	ds_read_b128 v[230:233], v224 offset:37888
	ds_read_b128 v[234:237], v224 offset:38912
	ds_read_b128 v[238:241], v224 offset:39936
	global_load_lds_dwordx4 v[248:249], off
	v_lshl_add_u64 v[248:249], s[24:25], 0, v[176:177]
	s_mov_b32 m0, s38
	s_nop 0
	global_load_lds_dwordx4 v[248:249], off
	s_waitcnt vmcnt(8)
	s_waitcnt lgkmcnt(0)
	s_barrier
	s_setprio 1
	s_waitcnt lgkmcnt(0)
	v_mfma_f32_16x16x32_bf16 v[126:129], v[130:133], v[162:165], v[126:129]
	v_mfma_f32_16x16x32_bf16 v[122:125], v[138:141], v[162:165], v[122:125]
	v_mfma_f32_16x16x32_bf16 v[118:121], v[130:133], v[194:197], v[118:121]
	v_mfma_f32_16x16x32_bf16 v[106:109], v[138:141], v[194:197], v[106:109]
	v_mfma_f32_16x16x32_bf16 v[94:97], v[130:133], v[226:229], v[94:97]
	v_mfma_f32_16x16x32_bf16 v[90:93], v[138:141], v[226:229], v[90:93]
	v_mfma_f32_16x16x32_bf16 v[86:89], v[130:133], v[234:237], v[86:89]
	v_mfma_f32_16x16x32_bf16 v[74:77], v[138:141], v[234:237], v[74:77]
	v_mfma_f32_16x16x32_bf16 v[126:129], v[134:137], v[190:193], v[126:129]
	v_mfma_f32_16x16x32_bf16 v[122:125], v[142:145], v[190:193], v[122:125]
	v_mfma_f32_16x16x32_bf16 v[118:121], v[134:137], v[198:201], v[118:121]
	v_mfma_f32_16x16x32_bf16 v[106:109], v[142:145], v[198:201], v[106:109]
	v_mfma_f32_16x16x32_bf16 v[94:97], v[134:137], v[230:233], v[94:97]
	v_mfma_f32_16x16x32_bf16 v[90:93], v[142:145], v[230:233], v[90:93]
	v_mfma_f32_16x16x32_bf16 v[86:89], v[134:137], v[238:241], v[86:89]
	v_mfma_f32_16x16x32_bf16 v[74:77], v[142:145], v[238:241], v[74:77]
	s_setprio 0
	s_setprio 1
	v_mfma_f32_16x16x32_bf16 v[114:117], v[146:149], v[162:165], v[114:117]
	v_mfma_f32_16x16x32_bf16 v[110:113], v[154:157], v[162:165], v[110:113]
	v_mfma_f32_16x16x32_bf16 v[102:105], v[146:149], v[194:197], v[102:105]
	v_mfma_f32_16x16x32_bf16 v[98:101], v[154:157], v[194:197], v[98:101]
	v_mfma_f32_16x16x32_bf16 v[82:85], v[146:149], v[226:229], v[82:85]
	v_mfma_f32_16x16x32_bf16 v[78:81], v[154:157], v[226:229], v[78:81]
	v_mfma_f32_16x16x32_bf16 v[70:73], v[146:149], v[234:237], v[70:73]
	v_mfma_f32_16x16x32_bf16 v[66:69], v[154:157], v[234:237], v[66:69]
	v_mfma_f32_16x16x32_bf16 v[114:117], v[150:153], v[190:193], v[114:117]
	v_mfma_f32_16x16x32_bf16 v[110:113], v[158:161], v[190:193], v[110:113]
	v_mfma_f32_16x16x32_bf16 v[102:105], v[150:153], v[198:201], v[102:105]
	v_mfma_f32_16x16x32_bf16 v[98:101], v[158:161], v[198:201], v[98:101]
	v_mfma_f32_16x16x32_bf16 v[82:85], v[150:153], v[230:233], v[82:85]
	v_mfma_f32_16x16x32_bf16 v[78:81], v[158:161], v[230:233], v[78:81]
	v_mfma_f32_16x16x32_bf16 v[70:73], v[150:153], v[238:241], v[70:73]
	v_mfma_f32_16x16x32_bf16 v[66:69], v[158:161], v[238:241], v[66:69]
	s_setprio 0
	s_barrier
; #define PG8_STAGE(bufoff, gbase, voff) do { _Pragma("unroll") for (int _i = 0; _i < 2; ++_i) \
;         __builtin_amdgcn_global_load_lds((const unsigned*)((const char*)(gbase) + (voff)[_i]), (LAS unsigned*)(lds + (bufoff) + ldsw + _i * 8192), 16, 0, 0); } while (0)
; #define PG8_LDA(dst, b, h) do { _Pragma("unroll") for (int m = 0; m < 4; ++m) _Pragma("unroll") for (int k = 0; k < 2; ++k) dst[m][k] = *(const LAS bf16x8*)(lds + PG8_SA(b, h) + aoff + m * 2048 + k * 1024); } while (0)
; #define PG8_MMA(ai, bj, At, Bt) do { __builtin_amdgcn_s_setprio(1); _Pragma("unroll") for (int m = 0; m < 4; ++m) _Pragma("unroll") for (int n = 0; n < 2; ++n) _Pragma("unroll") for (int k = 0; k < 2; ++k) \
;         acc[ai][bj][m][n] = __builtin_amdgcn_mfma_f32_16x16x32_bf16(Bt[n][k], At[m][k], acc[ai][bj][m][n], 0, 0, 0); __builtin_amdgcn_s_setprio(0); } while (0)
; #define PG8_WAIT_V(n) asm volatile("s_waitcnt vmcnt(" #n ")" ::: "memory")
; #define PG8_WAIT_L(n) asm volatile("s_waitcnt lgkmcnt(" #n ")" ::: "memory")
; #define PG8_BAR __builtin_amdgcn_s_barrier()
; #define PG8_SCHED __builtin_amdgcn_sched_barrier(0)
; template <class Epi>
; __device__ __forceinline__ void gemm_phase(LAS unsigned char* lds, const Sched& S, const Epi& E) {
;     ...
;         for (int t = 0; t < nt; t += 2) {
;             const bool last = (t == nt - 2);
;     ...
;             PG8_LDA(At, 1, 1); PG8_STAGE(PG8_SB(1, 0), b3, voffB); PG8_STAGE(PG8_SB(1, 1), b3 + hstepB, voffB); PG8_STAGE(PG8_SA(1, 0), a3, voffA);
;             PG8_WAIT_V(8); PG8_WAIT_L(0); PG8_BAR; PG8_MMA(1, 0, At, B0); PG8_MMA(1, 1, At, B1); PG8_BAR; PG8_SCHED;
	s_add_i32 s24, s72, s34
	v_lshl_add_u64 v[166:167], v[166:167], 0, s[0:1]
	s_mov_b32 m0, s24
	ds_read_b128 v[162:165], v224 offset:49152
	ds_read_b128 v[190:193], v224 offset:50176
	ds_read_b128 v[194:197], v224 offset:51200
	ds_read_b128 v[198:201], v224 offset:52224
	ds_read_b128 v[226:229], v224 offset:53248
	ds_read_b128 v[230:233], v224 offset:54272
	ds_read_b128 v[234:237], v224 offset:55296
	ds_read_b128 v[238:241], v224 offset:56320
	global_load_lds_dwordx4 v[166:167], off
	s_add_i32 m0, s24, 0x2000
	s_add_u32 s22, s22, 0x160080
	v_lshl_add_u64 v[166:167], v[242:243], 0, s[0:1]
	s_addc_u32 s23, s23, 0
	s_add_i32 s24, s73, s34
	global_load_lds_dwordx4 v[166:167], off
	v_lshl_add_u64 v[166:167], s[22:23], 0, v[168:169]
	s_mov_b32 m0, s24
	s_nop 0
	global_load_lds_dwordx4 v[166:167], off
	v_lshl_add_u64 v[166:167], s[22:23], 0, v[176:177]
	s_add_i32 m0, s24, 0x2000
	s_nop 0
	global_load_lds_dwordx4 v[166:167], off
	v_lshl_add_u64 v[166:167], v[244:245], 0, s[0:1]
	s_mov_b32 m0, s39
	s_nop 0
	global_load_lds_dwordx4 v[166:167], off
	v_lshl_add_u64 v[166:167], v[246:247], 0, s[0:1]
	s_mov_b32 m0, s58
	s_nop 0
	global_load_lds_dwordx4 v[166:167], off
	s_waitcnt vmcnt(8)
	s_waitcnt lgkmcnt(0)
	s_barrier
	s_setprio 1
	s_waitcnt lgkmcnt(0)
	v_mfma_f32_16x16x32_bf16 v[62:65], v[130:133], v[162:165], v[62:65]
	v_mfma_f32_16x16x32_bf16 v[58:61], v[138:141], v[162:165], v[58:61]
	v_mfma_f32_16x16x32_bf16 v[54:57], v[130:133], v[194:197], v[54:57]
	v_mfma_f32_16x16x32_bf16 v[42:45], v[138:141], v[194:197], v[42:45]
	v_mfma_f32_16x16x32_bf16 v[30:33], v[130:133], v[226:229], v[30:33]
	v_mfma_f32_16x16x32_bf16 v[26:29], v[138:141], v[226:229], v[26:29]
	v_mfma_f32_16x16x32_bf16 v[22:25], v[130:133], v[234:237], v[22:25]
	v_mfma_f32_16x16x32_bf16 v[10:13], v[138:141], v[234:237], v[10:13]
	v_mfma_f32_16x16x32_bf16 v[62:65], v[134:137], v[190:193], v[62:65]
	v_mfma_f32_16x16x32_bf16 v[58:61], v[142:145], v[190:193], v[58:61]
	v_mfma_f32_16x16x32_bf16 v[54:57], v[134:137], v[198:201], v[54:57]
	v_mfma_f32_16x16x32_bf16 v[42:45], v[142:145], v[198:201], v[42:45]
	v_mfma_f32_16x16x32_bf16 v[30:33], v[134:137], v[230:233], v[30:33]
	v_mfma_f32_16x16x32_bf16 v[26:29], v[142:145], v[230:233], v[26:29]
	v_mfma_f32_16x16x32_bf16 v[22:25], v[134:137], v[238:241], v[22:25]
	v_mfma_f32_16x16x32_bf16 v[10:13], v[142:145], v[238:241], v[10:13]
	s_setprio 0
	s_setprio 1
	v_mfma_f32_16x16x32_bf16 v[50:53], v[146:149], v[162:165], v[50:53]
	v_mfma_f32_16x16x32_bf16 v[46:49], v[154:157], v[162:165], v[46:49]
	v_mfma_f32_16x16x32_bf16 v[38:41], v[146:149], v[194:197], v[38:41]
	v_mfma_f32_16x16x32_bf16 v[34:37], v[154:157], v[194:197], v[34:37]
	v_mfma_f32_16x16x32_bf16 v[18:21], v[146:149], v[226:229], v[18:21]
	v_mfma_f32_16x16x32_bf16 v[14:17], v[154:157], v[226:229], v[14:17]
	v_mfma_f32_16x16x32_bf16 v[6:9], v[146:149], v[234:237], v[6:9]
	v_mfma_f32_16x16x32_bf16 v[2:5], v[154:157], v[234:237], v[2:5]
	v_mfma_f32_16x16x32_bf16 v[50:53], v[150:153], v[190:193], v[50:53]
	v_mfma_f32_16x16x32_bf16 v[46:49], v[158:161], v[190:193], v[46:49]
	v_mfma_f32_16x16x32_bf16 v[38:41], v[150:153], v[198:201], v[38:41]
	v_mfma_f32_16x16x32_bf16 v[34:37], v[158:161], v[198:201], v[34:37]
	v_mfma_f32_16x16x32_bf16 v[18:21], v[150:153], v[230:233], v[18:21]
	v_mfma_f32_16x16x32_bf16 v[14:17], v[158:161], v[230:233], v[14:17]
	v_mfma_f32_16x16x32_bf16 v[6:9], v[150:153], v[238:241], v[6:9]
	v_mfma_f32_16x16x32_bf16 v[2:5], v[158:161], v[238:241], v[2:5]
	s_setprio 0
	s_barrier
	s_add_u32 s4, s4, 0x100
	s_addc_u32 s5, s5, 0
	s_add_u32 vcc_lo, vcc_lo, 0x100
	s_addc_u32 vcc_hi, vcc_hi, 0
	s_cmp_ge_i32 s49, s94
	s_mov_b32 s22, s49
	s_cbranch_scc1 .Lpeel_exit_down

; #define PG8_BAR __builtin_amdgcn_s_barrier()
; template <class Epi>
; __device__ __forceinline__ void gemm_phase(LAS unsigned char* lds, const Sched& S, const Epi& E) {
;     ...
;         if (wr == 0) PG8_BAR;
;         E(acc, cur, wr, wc, fr, fq);
.Lpeel_exit_down:
	s_and_b64 vcc, exec, s[10:11]
	s_cbranch_vccz .LBB0_2394
	s_barrier
